# opt37: opt26 + EpiProj (G3) epilogue: eight sum-of-squares loads issued together up front, one wait instead of a load/wait/store ladder per row group (s_nop keeps the store-data wait states)
# speedup vs baseline: 1.0021x; 1.0021x over previous
; __device__ __forceinline__ unsigned cvt_pk_bf16(float lo, float hi) { f32x2_t v = {lo, hi}; bf16x2_t b = __builtin_convertvector(v, bf16x2_t); return __builtin_bit_cast(unsigned, b); }
; __device__ __forceinline__ float rstd_of(const float* ss, int row) { return __builtin_amdgcn_rsqf(ss[row] * (1.0f / 1024.0f) + RMS_EPS); }
;     __device__ __forceinline__ void operator()(const Acc& acc, const Unit& u, int wr, int wc, int fr, int fq) const {
;         const int row0 = u.pm * BM + wr * 64 + fr, cc = wc * 32 + 8 * fq;
;         const int tile = u.pn; const bool isq = (tile < 4) || (tile >= 8 && tile < 12), isg = tile >= 13;
;         float bv[2][8];
; #pragma unroll
;         for (int bj = 0; bj < 2; ++bj)
; #pragma unroll
;             for (int e = 0; e < 8; ++e) bv[bj][e] = isg ? bgate[(tile - 13) * BM + cc + bj * HALF + e] : 0.f;
;         const float sc = isq ? QSCALE : 1.0f;
; #pragma unroll
;         for (int ai = 0; ai < 2; ++ai)
; #pragma unroll
;             for (int m = 0; m < 4; ++m) {
;                 const int row = row0 + ai * HALF + m * 16; const float rs = rstd_of(ss, row) * sc;
;                 const int b = row >> 11, t = row & (SEQ - 1);
; #pragma unroll
;                 for (int bj = 0; bj < 2; ++bj) {
;                     float o[8];
; #pragma unroll
;                     for (int n = 0; n < 2; ++n)
; #pragma unroll
;                         for (int e = 0; e < 4; ++e) { float v = acc[ai][bj][m][n][e] * rs; if (isg) v = sigmoidf_(v + bv[bj][4 * n + e]); o[4 * n + e] = v; }
;                     u32x4 w; w.x = cvt_pk_bf16(o[0], o[1]); w.y = cvt_pk_bf16(o[2], o[3]); w.z = cvt_pk_bf16(o[4], o[5]); w.w = cvt_pk_bf16(o[6], o[7]);
;                     bf16_t* dst;
;                     if (tile < 4) dst = P + (size_t)row * PP + C_DQ + tile * BM + bj * HALF + cc;
;                     else if (tile < 8) dst = KD + ((size_t)((b * 8 + (tile - 4) * 2 + bj) * SEQ + t)) * 128 + cc;
;                     else if (tile < 12) dst = P + (size_t)row * PP + C_SQ + (tile - 8) * BM + bj * HALF + cc;
;                     else if (tile == 12) { const int ccf = bj * HALF + cc; dst = KS + ((size_t)((b * 4 + (ccf >> 6)) * SEQ + t)) * 64 + (ccf & 63); }
;                     else dst = P + (size_t)row * PP + C_GA + (tile - 13) * BM + bj * HALF + cc;
.LBB0_434:
	s_lshl_b32 s2, s88, 8
	s_add_i32 s6, s2, s75
	v_or_b32_e32 v152, s6, v139
	v_ashrrev_i32_e32 v153, 31, v152
	v_lshl_add_u64 v[154:155], v[152:153], 2, s[44:45]
	global_load_dword v220, v[154:155], off
	global_load_dword v221, v[154:155], off offset:64
	global_load_dword v222, v[154:155], off offset:128
	global_load_dword v223, v[154:155], off offset:192
	global_load_dword v224, v[154:155], off offset:512
	global_load_dword v225, v[154:155], off offset:576
	global_load_dword v226, v[154:155], off offset:640
	global_load_dword v227, v[154:155], off offset:704
	s_cmp_lt_i32 s14, 4
	s_cselect_b64 s[96:97], -1, 0
	s_cmp_gt_i32 s14, 3
	s_cselect_b64 s[12:13], -1, 0
	s_cmp_gt_u32 s14, 7
	s_cselect_b64 s[94:95], -1, 0
	s_cmp_gt_u32 s14, 11
	s_cselect_b64 s[90:91], -1, 0
	s_cmp_lg_u32 s14, 12
	s_cselect_b64 s[88:89], -1, 0
	s_ashr_i32 s3, s6, 11
	s_lshl_b32 s2, s14, 1
	s_lshl_b32 s7, s3, 13
	s_add_i32 s2, s2, -8
	s_or_b32 s17, s7, s23
	s_lshl_b32 s3, s3, 3
	v_bitop3_b32 v194, s6, v171, v139 bitop3:0xc8
	s_mov_b32 s87, s1
	s_add_i32 s3, s3, s2
	v_lshlrev_b64 v[158:159], 13, v[152:153]
	v_or_b32_e32 v156, s17, v194
	s_mov_b64 s[6:7], -1
	s_and_b64 vcc, exec, s[12:13]
	s_cbranch_vccz .LBB0_448
	s_and_b64 vcc, exec, s[94:95]
	s_cbranch_vccz .LBB0_445
	s_and_b64 vcc, exec, s[90:91]
	s_cbranch_vccz .LBB0_442
	s_and_b64 vcc, exec, s[88:89]
	s_cbranch_vccz .LBB0_439
	v_lshl_add_u64 v[162:163], s[20:21], 0, v[158:159]
	v_lshl_add_u64 v[162:163], s[0:1], 1, v[162:163]
	v_lshlrev_b32_e32 v136, 1, v138
	v_lshl_add_u64 v[162:163], v[162:163], 0, v[136:137]
	v_lshl_add_u64 v[164:165], v[162:163], 0, s[30:31]
	s_mov_b64 s[6:7], 0

; __device__ __forceinline__ unsigned cvt_pk_bf16(float lo, float hi) { f32x2_t v = {lo, hi}; bf16x2_t b = __builtin_convertvector(v, bf16x2_t); return __builtin_bit_cast(unsigned, b); }
; __device__ __forceinline__ float rstd_of(const float* ss, int row) { return __builtin_amdgcn_rsqf(ss[row] * (1.0f / 1024.0f) + RMS_EPS); }
; __device__ __forceinline__ float sigmoidf_(float v) { return __builtin_amdgcn_rcpf(1.0f + __builtin_amdgcn_exp2f(-v * LOG2E)); }
;     __device__ __forceinline__ void operator()(const Acc& acc, const Unit& u, int wr, int wc, int fr, int fq) const {
;     ...
;                 const int row = row0 + ai * HALF + m * 16; const float rs = rstd_of(ss, row) * sc;
;                 const int b = row >> 11, t = row & (SEQ - 1);
; #pragma unroll
;                 for (int bj = 0; bj < 2; ++bj) {
;                     float o[8];
; #pragma unroll
;                     for (int n = 0; n < 2; ++n)
; #pragma unroll
;                         for (int e = 0; e < 4; ++e) { float v = acc[ai][bj][m][n][e] * rs; if (isg) v = sigmoidf_(v + bv[bj][4 * n + e]); o[4 * n + e] = v; }
;                     u32x4 w; w.x = cvt_pk_bf16(o[0], o[1]); w.y = cvt_pk_bf16(o[2], o[3]); w.z = cvt_pk_bf16(o[4], o[5]); w.w = cvt_pk_bf16(o[6], o[7]);
;                     bf16_t* dst;
;                     if (tile < 4) dst = P + (size_t)row * PP + C_DQ + tile * BM + bj * HALF + cc;
;                     else if (tile < 8) dst = KD + ((size_t)((b * 8 + (tile - 4) * 2 + bj) * SEQ + t)) * 128 + cc;
;                     else if (tile < 12) dst = P + (size_t)row * PP + C_SQ + (tile - 8) * BM + bj * HALF + cc;
;                     else if (tile == 12) { const int ccf = bj * HALF + cc; dst = KS + ((size_t)((b * 4 + (ccf >> 6)) * SEQ + t)) * 64 + (ccf & 63); }
;                     else dst = P + (size_t)row * PP + C_GA + (tile - 13) * BM + bj * HALF + cc;
;                     *(u32x4*)dst = w;
.LBB0_450:
	s_and_b32 s6, s14, 0x7ffffffc
	s_waitcnt vmcnt(0)
	v_fmamk_f32 v157, v220, 0x3a800000, v170
	s_cmp_eq_u32 s6, 8
	v_rsq_f32_e32 v157, v157
	s_cselect_b64 s[6:7], -1, 0
	s_or_b64 vcc, s[96:97], s[6:7]
	v_cndmask_b32_e32 v153, 1.0, v173, vcc
	v_mul_f32_e32 v157, v153, v157
	v_mul_f32_e32 v179, v124, v157
	v_fma_f32 v124, v124, v157, v187
	v_mul_f32_e32 v124, 0xbfb8aa3b, v124
	v_exp_f32_e32 v124, v124
	v_readlane_b32 s70, v254, 54
	s_mov_b64 s[6:7], -1
	s_andn2_b64 vcc, exec, s[12:13]
	v_add_f32_e32 v124, 1.0, v124
	v_rcp_f32_e32 v124, v124
	v_readlane_b32 s69, v254, 53
	v_readlane_b32 s71, v254, 55
	v_cndmask_b32_e64 v124, v179, v124, s[10:11]
	v_mul_f32_e32 v179, v125, v157
	v_fma_f32 v125, v125, v157, v186
	v_mul_f32_e32 v125, 0xbfb8aa3b, v125
	v_exp_f32_e32 v125, v125
	s_nop 0
	v_add_f32_e32 v125, 1.0, v125
	v_rcp_f32_e32 v125, v125
	s_nop 0
	v_cndmask_b32_e64 v125, v179, v125, s[10:11]
	v_mul_f32_e32 v179, v126, v157
	v_fma_f32 v126, v126, v157, v191
	v_mul_f32_e32 v126, 0xbfb8aa3b, v126
	v_exp_f32_e32 v126, v126
	s_nop 0
	v_add_f32_e32 v126, 1.0, v126
	v_rcp_f32_e32 v126, v126
	s_nop 0
	v_cndmask_b32_e64 v126, v179, v126, s[10:11]
	v_mul_f32_e32 v179, v127, v157
	v_fma_f32 v127, v127, v157, v188
	v_mul_f32_e32 v127, 0xbfb8aa3b, v127
	v_exp_f32_e32 v127, v127
	s_nop 0
	v_add_f32_e32 v127, 1.0, v127
	v_rcp_f32_e32 v127, v127
	s_nop 0
	v_cndmask_b32_e64 v127, v179, v127, s[10:11]
	v_mul_f32_e32 v179, v120, v157
	v_fma_f32 v120, v120, v157, v192
	v_mul_f32_e32 v120, 0xbfb8aa3b, v120
	v_exp_f32_e32 v120, v120
	s_nop 0
	v_add_f32_e32 v120, 1.0, v120
	v_rcp_f32_e32 v120, v120
	s_nop 0
	v_cndmask_b32_e64 v179, v179, v120, s[10:11]
	v_mul_f32_e32 v120, v121, v157
	v_fma_f32 v121, v121, v157, v189
	v_mul_f32_e32 v121, 0xbfb8aa3b, v121
	v_exp_f32_e32 v121, v121
	s_nop 0
	v_add_f32_e32 v121, 1.0, v121
	v_rcp_f32_e32 v121, v121
	s_nop 0
	v_cndmask_b32_e64 v195, v120, v121, s[10:11]
	v_fma_f32 v121, v122, v157, v193
	v_mul_f32_e32 v121, 0xbfb8aa3b, v121
	v_exp_f32_e32 v121, v121
	v_mul_f32_e32 v120, v122, v157
	v_cvt_pk_bf16_f32 v122, v179, v195
	v_add_f32_e32 v121, 1.0, v121
	v_rcp_f32_e32 v121, v121
	s_nop 0
	v_cndmask_b32_e64 v196, v120, v121, s[10:11]
	v_fma_f32 v121, v123, v157, v190
	v_mul_f32_e32 v121, 0xbfb8aa3b, v121
	v_exp_f32_e32 v121, v121
	v_mul_f32_e32 v120, v123, v157
	v_add_f32_e32 v121, 1.0, v121
	v_rcp_f32_e32 v121, v121
	s_nop 0
	v_cndmask_b32_e64 v123, v120, v121, s[10:11]
	v_cvt_pk_bf16_f32 v120, v124, v125
	v_cvt_pk_bf16_f32 v121, v126, v127
	v_cvt_pk_bf16_f32 v123, v196, v123
	global_store_dwordx4 v[164:165], v[120:123], off
	s_nop 1
	v_cndmask_b32_e64 v120, 0, 1, s[12:13]
	v_cmp_ne_u32_e64 s[14:15], 1, v120
	v_cndmask_b32_e64 v120, 0, 1, s[94:95]
	v_cmp_ne_u32_e64 s[12:13], 1, v120
	s_cbranch_vccnz .LBB0_464
	s_and_b64 vcc, exec, s[12:13]
	s_cbranch_vccnz .LBB0_461
	s_andn2_b64 vcc, exec, s[90:91]
	s_cbranch_vccnz .LBB0_458
	s_andn2_b64 vcc, exec, s[88:89]
	s_cbranch_vccnz .LBB0_455
	v_lshl_add_u64 v[120:121], s[0:1], 1, v[162:163]
	v_lshl_add_u64 v[120:121], v[120:121], 0, v[136:137]
	v_lshl_add_u64 v[120:121], v[120:121], 0, s[36:37]
	s_mov_b64 s[6:7], 0

; __device__ __forceinline__ unsigned cvt_pk_bf16(float lo, float hi) { f32x2_t v = {lo, hi}; bf16x2_t b = __builtin_convertvector(v, bf16x2_t); return __builtin_bit_cast(unsigned, b); }
; __device__ __forceinline__ float rstd_of(const float* ss, int row) { return __builtin_amdgcn_rsqf(ss[row] * (1.0f / 1024.0f) + RMS_EPS); }
; __device__ __forceinline__ float sigmoidf_(float v) { return __builtin_amdgcn_rcpf(1.0f + __builtin_amdgcn_exp2f(-v * LOG2E)); }
;     __device__ __forceinline__ void operator()(const Acc& acc, const Unit& u, int wr, int wc, int fr, int fq) const {
;     ...
;                 const int row = row0 + ai * HALF + m * 16; const float rs = rstd_of(ss, row) * sc;
;                 const int b = row >> 11, t = row & (SEQ - 1);
;     ...
;                 for (int bj = 0; bj < 2; ++bj) {
;                     float o[8];
; #pragma unroll
;                     for (int n = 0; n < 2; ++n)
; #pragma unroll
;                         for (int e = 0; e < 4; ++e) { float v = acc[ai][bj][m][n][e] * rs; if (isg) v = sigmoidf_(v + bv[bj][4 * n + e]); o[4 * n + e] = v; }
;                     u32x4 w; w.x = cvt_pk_bf16(o[0], o[1]); w.y = cvt_pk_bf16(o[2], o[3]); w.z = cvt_pk_bf16(o[4], o[5]); w.w = cvt_pk_bf16(o[6], o[7]);
;                     bf16_t* dst;
;                     if (tile < 4) dst = P + (size_t)row * PP + C_DQ + tile * BM + bj * HALF + cc;
;                     else if (tile < 8) dst = KD + ((size_t)((b * 8 + (tile - 4) * 2 + bj) * SEQ + t)) * 128 + cc;
;                     else if (tile < 12) dst = P + (size_t)row * PP + C_SQ + (tile - 8) * BM + bj * HALF + cc;
;                     else if (tile == 12) { const int ccf = bj * HALF + cc; dst = KS + ((size_t)((b * 4 + (ccf >> 6)) * SEQ + t)) * 64 + (ccf & 63); }
;                     else dst = P + (size_t)row * PP + C_GA + (tile - 13) * BM + bj * HALF + cc;
;                     *(u32x4*)dst = w;
.LBB0_466:
	v_mul_f32_e32 v122, v116, v157
	v_fma_f32 v116, v116, v157, v181
	v_mul_f32_e32 v116, 0xbfb8aa3b, v116
	v_exp_f32_e32 v116, v116
	s_movk_i32 s6, 0x7df
	s_mov_b64 s[94:95], -1
	s_and_b64 vcc, exec, s[14:15]
	v_add_f32_e32 v116, 1.0, v116
	v_rcp_f32_e32 v116, v116
	s_nop 0
	v_cndmask_b32_e64 v116, v122, v116, s[10:11]
	v_mul_f32_e32 v122, v117, v157
	v_fma_f32 v117, v117, v157, v174
	v_mul_f32_e32 v117, 0xbfb8aa3b, v117
	v_exp_f32_e32 v117, v117
	s_nop 0
	v_add_f32_e32 v117, 1.0, v117
	v_rcp_f32_e32 v117, v117
	s_nop 0
	v_cndmask_b32_e64 v117, v122, v117, s[10:11]
	v_mul_f32_e32 v122, v118, v157
	v_fma_f32 v118, v118, v157, v183
	v_mul_f32_e32 v118, 0xbfb8aa3b, v118
	v_exp_f32_e32 v118, v118
	s_nop 0
	v_add_f32_e32 v118, 1.0, v118
	v_rcp_f32_e32 v118, v118
	s_nop 0
	v_cndmask_b32_e64 v118, v122, v118, s[10:11]
	v_mul_f32_e32 v122, v119, v157
	v_fma_f32 v119, v119, v157, v178
	v_mul_f32_e32 v119, 0xbfb8aa3b, v119
	v_exp_f32_e32 v119, v119
	s_nop 0
	v_add_f32_e32 v119, 1.0, v119
	v_rcp_f32_e32 v119, v119
	s_nop 0
	v_cndmask_b32_e64 v119, v122, v119, s[10:11]
	v_mul_f32_e32 v122, v112, v157
	v_fma_f32 v112, v112, v157, v184
	v_mul_f32_e32 v112, 0xbfb8aa3b, v112
	v_exp_f32_e32 v112, v112
	s_nop 0
	v_add_f32_e32 v112, 1.0, v112
	v_rcp_f32_e32 v112, v112
	s_nop 0
	v_cndmask_b32_e64 v122, v122, v112, s[10:11]
	v_mul_f32_e32 v112, v113, v157
	v_fma_f32 v113, v113, v157, v180
	v_mul_f32_e32 v113, 0xbfb8aa3b, v113
	v_exp_f32_e32 v113, v113
	s_nop 0
	v_add_f32_e32 v113, 1.0, v113
	v_rcp_f32_e32 v113, v113
	s_nop 0
	v_cndmask_b32_e64 v123, v112, v113, s[10:11]
	v_fma_f32 v113, v114, v157, v185
	v_mul_f32_e32 v113, 0xbfb8aa3b, v113
	v_exp_f32_e32 v113, v113
	v_mul_f32_e32 v112, v114, v157
	v_cvt_pk_bf16_f32 v114, v122, v123
	v_add_f32_e32 v113, 1.0, v113
	v_rcp_f32_e32 v113, v113
	s_nop 0
	v_cndmask_b32_e64 v124, v112, v113, s[10:11]
	v_fma_f32 v113, v115, v157, v182
	v_mul_f32_e32 v113, 0xbfb8aa3b, v113
	v_exp_f32_e32 v113, v113
	v_mul_f32_e32 v112, v115, v157
	v_add_f32_e32 v113, 1.0, v113
	v_rcp_f32_e32 v113, v113
	s_nop 0
	v_cndmask_b32_e64 v115, v112, v113, s[10:11]
	v_cvt_pk_bf16_f32 v112, v116, v117
	v_cvt_pk_bf16_f32 v113, v118, v119
	v_cvt_pk_bf16_f32 v115, v124, v115
	global_store_dwordx4 v[120:121], v[112:115], off
	v_bitop3_b32 v120, v152, s6, 16 bitop3:0xc8
	s_nop 0
	v_or_b32_e32 v112, 16, v152
	v_ashrrev_i32_e32 v113, 31, v112
	v_lshl_add_u64 v[114:115], v[112:113], 2, s[44:45]
	s_nop 0
	v_lshlrev_b64 v[114:115], 13, v[112:113]
	v_or_b32_e32 v112, s17, v120
	s_cbranch_vccnz .LBB0_480
	s_and_b64 vcc, exec, s[12:13]
	s_mov_b64 s[6:7], -1
	s_cbranch_vccnz .LBB0_477
	s_andn2_b64 vcc, exec, s[90:91]
	s_cbranch_vccnz .LBB0_474
	s_andn2_b64 vcc, exec, s[88:89]
	s_cbranch_vccnz .LBB0_471
	v_lshl_add_u64 v[116:117], s[20:21], 0, v[114:115]
	v_lshl_add_u64 v[116:117], s[0:1], 1, v[116:117]
	v_lshl_add_u64 v[116:117], v[116:117], 0, v[136:137]
	v_lshl_add_u64 v[118:119], v[116:117], 0, s[30:31]
	s_mov_b64 s[6:7], 0

; __device__ __forceinline__ float rstd_of(const float* ss, int row) { return __builtin_amdgcn_rsqf(ss[row] * (1.0f / 1024.0f) + RMS_EPS); }
;     __device__ __forceinline__ void operator()(const Acc& acc, const Unit& u, int wr, int wc, int fr, int fq) const {
;     ...
;                 const int row = row0 + ai * HALF + m * 16; const float rs = rstd_of(ss, row) * sc;
;                 const int b = row >> 11, t = row & (SEQ - 1);
.LBB0_482:

; __device__ __forceinline__ unsigned cvt_pk_bf16(float lo, float hi) { f32x2_t v = {lo, hi}; bf16x2_t b = __builtin_convertvector(v, bf16x2_t); return __builtin_bit_cast(unsigned, b); }
; __device__ __forceinline__ float rstd_of(const float* ss, int row) { return __builtin_amdgcn_rsqf(ss[row] * (1.0f / 1024.0f) + RMS_EPS); }
; __device__ __forceinline__ float sigmoidf_(float v) { return __builtin_amdgcn_rcpf(1.0f + __builtin_amdgcn_exp2f(-v * LOG2E)); }
;     __device__ __forceinline__ void operator()(const Acc& acc, const Unit& u, int wr, int wc, int fr, int fq) const {
;     ...
;                 const int row = row0 + ai * HALF + m * 16; const float rs = rstd_of(ss, row) * sc;
;                 const int b = row >> 11, t = row & (SEQ - 1);
; #pragma unroll
;                 for (int bj = 0; bj < 2; ++bj) {
;                     float o[8];
; #pragma unroll
;                     for (int n = 0; n < 2; ++n)
; #pragma unroll
;                         for (int e = 0; e < 4; ++e) { float v = acc[ai][bj][m][n][e] * rs; if (isg) v = sigmoidf_(v + bv[bj][4 * n + e]); o[4 * n + e] = v; }
;                     u32x4 w; w.x = cvt_pk_bf16(o[0], o[1]); w.y = cvt_pk_bf16(o[2], o[3]); w.z = cvt_pk_bf16(o[4], o[5]); w.w = cvt_pk_bf16(o[6], o[7]);
;                     bf16_t* dst;
;                     if (tile < 4) dst = P + (size_t)row * PP + C_DQ + tile * BM + bj * HALF + cc;
;                     else if (tile < 8) dst = KD + ((size_t)((b * 8 + (tile - 4) * 2 + bj) * SEQ + t)) * 128 + cc;
;                     else if (tile < 12) dst = P + (size_t)row * PP + C_SQ + (tile - 8) * BM + bj * HALF + cc;
;                     else if (tile == 12) { const int ccf = bj * HALF + cc; dst = KS + ((size_t)((b * 4 + (ccf >> 6)) * SEQ + t)) * 64 + (ccf & 63); }
;                     else dst = P + (size_t)row * PP + C_GA + (tile - 13) * BM + bj * HALF + cc;
;                     *(u32x4*)dst = w;
	v_fmamk_f32 v113, v221, 0x3a800000, v170
	v_rsq_f32_e32 v113, v113
	s_mov_b64 s[94:95], -1
	s_and_b64 vcc, exec, s[14:15]
	v_mul_f32_e32 v113, v153, v113
	v_mul_f32_e32 v121, v108, v113
	v_fma_f32 v108, v108, v113, v187
	v_mul_f32_e32 v108, 0xbfb8aa3b, v108
	v_exp_f32_e32 v108, v108
	s_nop 0
	v_add_f32_e32 v108, 1.0, v108
	v_rcp_f32_e32 v108, v108
	s_nop 0
	v_cndmask_b32_e64 v108, v121, v108, s[10:11]
	v_mul_f32_e32 v121, v109, v113
	v_fma_f32 v109, v109, v113, v186
	v_mul_f32_e32 v109, 0xbfb8aa3b, v109
	v_exp_f32_e32 v109, v109
	s_nop 0
	v_add_f32_e32 v109, 1.0, v109
	v_rcp_f32_e32 v109, v109
	s_nop 0
	v_cndmask_b32_e64 v109, v121, v109, s[10:11]
	v_mul_f32_e32 v121, v110, v113
	v_fma_f32 v110, v110, v113, v191
	v_mul_f32_e32 v110, 0xbfb8aa3b, v110
	v_exp_f32_e32 v110, v110
	s_nop 0
	v_add_f32_e32 v110, 1.0, v110
	v_rcp_f32_e32 v110, v110
	s_nop 0
	v_cndmask_b32_e64 v110, v121, v110, s[10:11]
	v_mul_f32_e32 v121, v111, v113
	v_fma_f32 v111, v111, v113, v188
	v_mul_f32_e32 v111, 0xbfb8aa3b, v111
	v_exp_f32_e32 v111, v111
	s_nop 0
	v_add_f32_e32 v111, 1.0, v111
	v_rcp_f32_e32 v111, v111
	s_nop 0
	v_cndmask_b32_e64 v111, v121, v111, s[10:11]
	v_mul_f32_e32 v121, v104, v113
	v_fma_f32 v104, v104, v113, v192
	v_mul_f32_e32 v104, 0xbfb8aa3b, v104
	v_exp_f32_e32 v104, v104
	s_nop 0
	v_add_f32_e32 v104, 1.0, v104
	v_rcp_f32_e32 v104, v104
	s_nop 0
	v_cndmask_b32_e64 v121, v121, v104, s[10:11]
	v_mul_f32_e32 v104, v105, v113
	v_fma_f32 v105, v105, v113, v189
	v_mul_f32_e32 v105, 0xbfb8aa3b, v105
	v_exp_f32_e32 v105, v105
	s_nop 0
	v_add_f32_e32 v105, 1.0, v105
	v_rcp_f32_e32 v105, v105
	s_nop 0
	v_cndmask_b32_e64 v122, v104, v105, s[10:11]
	v_fma_f32 v105, v106, v113, v193
	v_mul_f32_e32 v105, 0xbfb8aa3b, v105
	v_exp_f32_e32 v105, v105
	v_mul_f32_e32 v104, v106, v113
	v_cvt_pk_bf16_f32 v106, v121, v122
	v_add_f32_e32 v105, 1.0, v105
	v_rcp_f32_e32 v105, v105
	s_nop 0
	v_cndmask_b32_e64 v123, v104, v105, s[10:11]
	v_fma_f32 v105, v107, v113, v190
	v_mul_f32_e32 v105, 0xbfb8aa3b, v105
	v_exp_f32_e32 v105, v105
	v_mul_f32_e32 v104, v107, v113
	v_add_f32_e32 v105, 1.0, v105
	v_rcp_f32_e32 v105, v105
	s_nop 0
	v_cndmask_b32_e64 v107, v104, v105, s[10:11]
	v_cvt_pk_bf16_f32 v104, v108, v109
	v_cvt_pk_bf16_f32 v105, v110, v111
	v_cvt_pk_bf16_f32 v107, v123, v107
	global_store_dwordx4 v[118:119], v[104:107], off
	s_cbranch_vccnz .LBB0_496
	s_and_b64 vcc, exec, s[12:13]
	s_mov_b64 s[6:7], -1
	s_cbranch_vccnz .LBB0_493
	s_andn2_b64 vcc, exec, s[90:91]
	s_cbranch_vccnz .LBB0_490
	s_andn2_b64 vcc, exec, s[88:89]
	s_cbranch_vccnz .LBB0_487
	v_lshl_add_u64 v[104:105], s[0:1], 1, v[116:117]
	v_lshl_add_u64 v[104:105], v[104:105], 0, v[136:137]
	v_lshl_add_u64 v[104:105], v[104:105], 0, s[36:37]
	s_mov_b64 s[6:7], 0

; __device__ __forceinline__ unsigned cvt_pk_bf16(float lo, float hi) { f32x2_t v = {lo, hi}; bf16x2_t b = __builtin_convertvector(v, bf16x2_t); return __builtin_bit_cast(unsigned, b); }
; __device__ __forceinline__ float rstd_of(const float* ss, int row) { return __builtin_amdgcn_rsqf(ss[row] * (1.0f / 1024.0f) + RMS_EPS); }
; __device__ __forceinline__ float sigmoidf_(float v) { return __builtin_amdgcn_rcpf(1.0f + __builtin_amdgcn_exp2f(-v * LOG2E)); }
;     __device__ __forceinline__ void operator()(const Acc& acc, const Unit& u, int wr, int wc, int fr, int fq) const {
;     ...
;                 const int row = row0 + ai * HALF + m * 16; const float rs = rstd_of(ss, row) * sc;
;                 const int b = row >> 11, t = row & (SEQ - 1);
;     ...
;                 for (int bj = 0; bj < 2; ++bj) {
;                     float o[8];
; #pragma unroll
;                     for (int n = 0; n < 2; ++n)
; #pragma unroll
;                         for (int e = 0; e < 4; ++e) { float v = acc[ai][bj][m][n][e] * rs; if (isg) v = sigmoidf_(v + bv[bj][4 * n + e]); o[4 * n + e] = v; }
;                     u32x4 w; w.x = cvt_pk_bf16(o[0], o[1]); w.y = cvt_pk_bf16(o[2], o[3]); w.z = cvt_pk_bf16(o[4], o[5]); w.w = cvt_pk_bf16(o[6], o[7]);
;                     bf16_t* dst;
;                     if (tile < 4) dst = P + (size_t)row * PP + C_DQ + tile * BM + bj * HALF + cc;
;                     else if (tile < 8) dst = KD + ((size_t)((b * 8 + (tile - 4) * 2 + bj) * SEQ + t)) * 128 + cc;
;                     else if (tile < 12) dst = P + (size_t)row * PP + C_SQ + (tile - 8) * BM + bj * HALF + cc;
;                     else if (tile == 12) { const int ccf = bj * HALF + cc; dst = KS + ((size_t)((b * 4 + (ccf >> 6)) * SEQ + t)) * 64 + (ccf & 63); }
;                     else dst = P + (size_t)row * PP + C_GA + (tile - 13) * BM + bj * HALF + cc;
;                     *(u32x4*)dst = w;
.LBB0_498:
	v_mul_f32_e32 v106, v100, v113
	v_fma_f32 v100, v100, v113, v181
	v_mul_f32_e32 v100, 0xbfb8aa3b, v100
	v_exp_f32_e32 v100, v100
	s_movk_i32 s6, 0x7ef
	s_mov_b64 s[94:95], -1
	s_and_b64 vcc, exec, s[14:15]
	v_add_f32_e32 v100, 1.0, v100
	v_rcp_f32_e32 v100, v100
	s_nop 0
	v_cndmask_b32_e64 v100, v106, v100, s[10:11]
	v_mul_f32_e32 v106, v101, v113
	v_fma_f32 v101, v101, v113, v174
	v_mul_f32_e32 v101, 0xbfb8aa3b, v101
	v_exp_f32_e32 v101, v101
	s_nop 0
	v_add_f32_e32 v101, 1.0, v101
	v_rcp_f32_e32 v101, v101
	s_nop 0
	v_cndmask_b32_e64 v101, v106, v101, s[10:11]
	v_mul_f32_e32 v106, v102, v113
	v_fma_f32 v102, v102, v113, v183
	v_mul_f32_e32 v102, 0xbfb8aa3b, v102
	v_exp_f32_e32 v102, v102
	s_nop 0
	v_add_f32_e32 v102, 1.0, v102
	v_rcp_f32_e32 v102, v102
	s_nop 0
	v_cndmask_b32_e64 v102, v106, v102, s[10:11]
	v_mul_f32_e32 v106, v103, v113
	v_fma_f32 v103, v103, v113, v178
	v_mul_f32_e32 v103, 0xbfb8aa3b, v103
	v_exp_f32_e32 v103, v103
	s_nop 0
	v_add_f32_e32 v103, 1.0, v103
	v_rcp_f32_e32 v103, v103
	s_nop 0
	v_cndmask_b32_e64 v103, v106, v103, s[10:11]
	v_mul_f32_e32 v106, v96, v113
	v_fma_f32 v96, v96, v113, v184
	v_mul_f32_e32 v96, 0xbfb8aa3b, v96
	v_exp_f32_e32 v96, v96
	s_nop 0
	v_add_f32_e32 v96, 1.0, v96
	v_rcp_f32_e32 v96, v96
	s_nop 0
	v_cndmask_b32_e64 v106, v106, v96, s[10:11]
	v_mul_f32_e32 v96, v97, v113
	v_fma_f32 v97, v97, v113, v180
	v_mul_f32_e32 v97, 0xbfb8aa3b, v97
	v_exp_f32_e32 v97, v97
	s_nop 0
	v_add_f32_e32 v97, 1.0, v97
	v_rcp_f32_e32 v97, v97
	s_nop 0
	v_cndmask_b32_e64 v107, v96, v97, s[10:11]
	v_fma_f32 v97, v98, v113, v185
	v_mul_f32_e32 v97, 0xbfb8aa3b, v97
	v_exp_f32_e32 v97, v97
	v_mul_f32_e32 v96, v98, v113
	v_cvt_pk_bf16_f32 v98, v106, v107
	v_add_f32_e32 v97, 1.0, v97
	v_rcp_f32_e32 v97, v97
	s_nop 0
	v_cndmask_b32_e64 v108, v96, v97, s[10:11]
	v_fma_f32 v97, v99, v113, v182
	v_mul_f32_e32 v97, 0xbfb8aa3b, v97
	v_exp_f32_e32 v97, v97
	v_mul_f32_e32 v96, v99, v113
	v_add_f32_e32 v97, 1.0, v97
	v_rcp_f32_e32 v97, v97
	s_nop 0
	v_cndmask_b32_e64 v99, v96, v97, s[10:11]
	v_cvt_pk_bf16_f32 v96, v100, v101
	v_cvt_pk_bf16_f32 v97, v102, v103
	v_cvt_pk_bf16_f32 v99, v108, v99
	global_store_dwordx4 v[104:105], v[96:99], off
	v_bitop3_b32 v104, v152, s6, 32 bitop3:0xc8
	s_nop 0
	v_or_b32_e32 v96, 32, v152
	v_ashrrev_i32_e32 v97, 31, v96
	v_lshl_add_u64 v[98:99], v[96:97], 2, s[44:45]
	s_nop 0
	v_lshlrev_b64 v[98:99], 13, v[96:97]
	v_or_b32_e32 v96, s17, v104
	s_cbranch_vccnz .LBB0_512
	s_and_b64 vcc, exec, s[12:13]
	s_mov_b64 s[6:7], -1
	s_cbranch_vccnz .LBB0_509
	s_andn2_b64 vcc, exec, s[90:91]
	s_cbranch_vccnz .LBB0_506
	s_andn2_b64 vcc, exec, s[88:89]
	s_cbranch_vccnz .LBB0_503
	v_lshl_add_u64 v[100:101], s[20:21], 0, v[98:99]
	v_lshl_add_u64 v[100:101], s[0:1], 1, v[100:101]
	v_lshl_add_u64 v[100:101], v[100:101], 0, v[136:137]
	v_lshl_add_u64 v[102:103], v[100:101], 0, s[30:31]
	s_mov_b64 s[6:7], 0

; __device__ __forceinline__ float rstd_of(const float* ss, int row) { return __builtin_amdgcn_rsqf(ss[row] * (1.0f / 1024.0f) + RMS_EPS); }
;     __device__ __forceinline__ void operator()(const Acc& acc, const Unit& u, int wr, int wc, int fr, int fq) const {
;     ...
;                 const int row = row0 + ai * HALF + m * 16; const float rs = rstd_of(ss, row) * sc;
;                 const int b = row >> 11, t = row & (SEQ - 1);
.LBB0_514:

; __device__ __forceinline__ unsigned cvt_pk_bf16(float lo, float hi) { f32x2_t v = {lo, hi}; bf16x2_t b = __builtin_convertvector(v, bf16x2_t); return __builtin_bit_cast(unsigned, b); }
; __device__ __forceinline__ float rstd_of(const float* ss, int row) { return __builtin_amdgcn_rsqf(ss[row] * (1.0f / 1024.0f) + RMS_EPS); }
; __device__ __forceinline__ float sigmoidf_(float v) { return __builtin_amdgcn_rcpf(1.0f + __builtin_amdgcn_exp2f(-v * LOG2E)); }
;     __device__ __forceinline__ void operator()(const Acc& acc, const Unit& u, int wr, int wc, int fr, int fq) const {
;     ...
;                 const int row = row0 + ai * HALF + m * 16; const float rs = rstd_of(ss, row) * sc;
;                 const int b = row >> 11, t = row & (SEQ - 1);
; #pragma unroll
;                 for (int bj = 0; bj < 2; ++bj) {
;                     float o[8];
; #pragma unroll
;                     for (int n = 0; n < 2; ++n)
; #pragma unroll
;                         for (int e = 0; e < 4; ++e) { float v = acc[ai][bj][m][n][e] * rs; if (isg) v = sigmoidf_(v + bv[bj][4 * n + e]); o[4 * n + e] = v; }
;                     u32x4 w; w.x = cvt_pk_bf16(o[0], o[1]); w.y = cvt_pk_bf16(o[2], o[3]); w.z = cvt_pk_bf16(o[4], o[5]); w.w = cvt_pk_bf16(o[6], o[7]);
;                     bf16_t* dst;
;                     if (tile < 4) dst = P + (size_t)row * PP + C_DQ + tile * BM + bj * HALF + cc;
;                     else if (tile < 8) dst = KD + ((size_t)((b * 8 + (tile - 4) * 2 + bj) * SEQ + t)) * 128 + cc;
;                     else if (tile < 12) dst = P + (size_t)row * PP + C_SQ + (tile - 8) * BM + bj * HALF + cc;
;                     else if (tile == 12) { const int ccf = bj * HALF + cc; dst = KS + ((size_t)((b * 4 + (ccf >> 6)) * SEQ + t)) * 64 + (ccf & 63); }
;                     else dst = P + (size_t)row * PP + C_GA + (tile - 13) * BM + bj * HALF + cc;
;                     *(u32x4*)dst = w;
	v_fmamk_f32 v97, v222, 0x3a800000, v170
	v_rsq_f32_e32 v97, v97
	s_mov_b64 s[94:95], -1
	s_and_b64 vcc, exec, s[14:15]
	v_mul_f32_e32 v97, v153, v97
	v_mul_f32_e32 v105, v92, v97
	v_fma_f32 v92, v92, v97, v187
	v_mul_f32_e32 v92, 0xbfb8aa3b, v92
	v_exp_f32_e32 v92, v92
	s_nop 0
	v_add_f32_e32 v92, 1.0, v92
	v_rcp_f32_e32 v92, v92
	s_nop 0
	v_cndmask_b32_e64 v92, v105, v92, s[10:11]
	v_mul_f32_e32 v105, v93, v97
	v_fma_f32 v93, v93, v97, v186
	v_mul_f32_e32 v93, 0xbfb8aa3b, v93
	v_exp_f32_e32 v93, v93
	s_nop 0
	v_add_f32_e32 v93, 1.0, v93
	v_rcp_f32_e32 v93, v93
	s_nop 0
	v_cndmask_b32_e64 v93, v105, v93, s[10:11]
	v_mul_f32_e32 v105, v94, v97
	v_fma_f32 v94, v94, v97, v191
	v_mul_f32_e32 v94, 0xbfb8aa3b, v94
	v_exp_f32_e32 v94, v94
	s_nop 0
	v_add_f32_e32 v94, 1.0, v94
	v_rcp_f32_e32 v94, v94
	s_nop 0
	v_cndmask_b32_e64 v94, v105, v94, s[10:11]
	v_mul_f32_e32 v105, v95, v97
	v_fma_f32 v95, v95, v97, v188
	v_mul_f32_e32 v95, 0xbfb8aa3b, v95
	v_exp_f32_e32 v95, v95
	s_nop 0
	v_add_f32_e32 v95, 1.0, v95
	v_rcp_f32_e32 v95, v95
	s_nop 0
	v_cndmask_b32_e64 v95, v105, v95, s[10:11]
	v_mul_f32_e32 v105, v88, v97
	v_fma_f32 v88, v88, v97, v192
	v_mul_f32_e32 v88, 0xbfb8aa3b, v88
	v_exp_f32_e32 v88, v88
	s_nop 0
	v_add_f32_e32 v88, 1.0, v88
	v_rcp_f32_e32 v88, v88
	s_nop 0
	v_cndmask_b32_e64 v105, v105, v88, s[10:11]
	v_mul_f32_e32 v88, v89, v97
	v_fma_f32 v89, v89, v97, v189
	v_mul_f32_e32 v89, 0xbfb8aa3b, v89
	v_exp_f32_e32 v89, v89
	s_nop 0
	v_add_f32_e32 v89, 1.0, v89
	v_rcp_f32_e32 v89, v89
	s_nop 0
	v_cndmask_b32_e64 v106, v88, v89, s[10:11]
	v_fma_f32 v89, v90, v97, v193
	v_mul_f32_e32 v89, 0xbfb8aa3b, v89
	v_exp_f32_e32 v89, v89
	v_mul_f32_e32 v88, v90, v97
	v_cvt_pk_bf16_f32 v90, v105, v106
	v_add_f32_e32 v89, 1.0, v89
	v_rcp_f32_e32 v89, v89
	s_nop 0
	v_cndmask_b32_e64 v107, v88, v89, s[10:11]
	v_fma_f32 v89, v91, v97, v190
	v_mul_f32_e32 v89, 0xbfb8aa3b, v89
	v_exp_f32_e32 v89, v89
	v_mul_f32_e32 v88, v91, v97
	v_add_f32_e32 v89, 1.0, v89
	v_rcp_f32_e32 v89, v89
	s_nop 0
	v_cndmask_b32_e64 v91, v88, v89, s[10:11]
	v_cvt_pk_bf16_f32 v88, v92, v93
	v_cvt_pk_bf16_f32 v89, v94, v95
	v_cvt_pk_bf16_f32 v91, v107, v91
	global_store_dwordx4 v[102:103], v[88:91], off
	s_cbranch_vccnz .LBB0_528
	s_and_b64 vcc, exec, s[12:13]
	s_mov_b64 s[6:7], -1
	s_cbranch_vccnz .LBB0_525
	s_andn2_b64 vcc, exec, s[90:91]
	s_cbranch_vccnz .LBB0_522
	s_andn2_b64 vcc, exec, s[88:89]
	s_cbranch_vccnz .LBB0_519
	v_lshl_add_u64 v[88:89], s[0:1], 1, v[100:101]
	v_lshl_add_u64 v[88:89], v[88:89], 0, v[136:137]
	v_lshl_add_u64 v[88:89], v[88:89], 0, s[36:37]
	s_mov_b64 s[6:7], 0

; __device__ __forceinline__ unsigned cvt_pk_bf16(float lo, float hi) { f32x2_t v = {lo, hi}; bf16x2_t b = __builtin_convertvector(v, bf16x2_t); return __builtin_bit_cast(unsigned, b); }
; __device__ __forceinline__ float rstd_of(const float* ss, int row) { return __builtin_amdgcn_rsqf(ss[row] * (1.0f / 1024.0f) + RMS_EPS); }
; __device__ __forceinline__ float sigmoidf_(float v) { return __builtin_amdgcn_rcpf(1.0f + __builtin_amdgcn_exp2f(-v * LOG2E)); }
;     __device__ __forceinline__ void operator()(const Acc& acc, const Unit& u, int wr, int wc, int fr, int fq) const {
;     ...
;                 const int row = row0 + ai * HALF + m * 16; const float rs = rstd_of(ss, row) * sc;
;                 const int b = row >> 11, t = row & (SEQ - 1);
;     ...
;                 for (int bj = 0; bj < 2; ++bj) {
;                     float o[8];
; #pragma unroll
;                     for (int n = 0; n < 2; ++n)
; #pragma unroll
;                         for (int e = 0; e < 4; ++e) { float v = acc[ai][bj][m][n][e] * rs; if (isg) v = sigmoidf_(v + bv[bj][4 * n + e]); o[4 * n + e] = v; }
;                     u32x4 w; w.x = cvt_pk_bf16(o[0], o[1]); w.y = cvt_pk_bf16(o[2], o[3]); w.z = cvt_pk_bf16(o[4], o[5]); w.w = cvt_pk_bf16(o[6], o[7]);
;                     bf16_t* dst;
;                     if (tile < 4) dst = P + (size_t)row * PP + C_DQ + tile * BM + bj * HALF + cc;
;                     else if (tile < 8) dst = KD + ((size_t)((b * 8 + (tile - 4) * 2 + bj) * SEQ + t)) * 128 + cc;
;                     else if (tile < 12) dst = P + (size_t)row * PP + C_SQ + (tile - 8) * BM + bj * HALF + cc;
;                     else if (tile == 12) { const int ccf = bj * HALF + cc; dst = KS + ((size_t)((b * 4 + (ccf >> 6)) * SEQ + t)) * 64 + (ccf & 63); }
;                     else dst = P + (size_t)row * PP + C_GA + (tile - 13) * BM + bj * HALF + cc;
;                     *(u32x4*)dst = w;
.LBB0_530:
	v_mul_f32_e32 v90, v84, v97
	v_fma_f32 v84, v84, v97, v181
	v_mul_f32_e32 v84, 0xbfb8aa3b, v84
	v_exp_f32_e32 v84, v84
	s_movk_i32 s6, 0x7ff
	s_mov_b64 s[94:95], -1
	s_and_b64 vcc, exec, s[14:15]
	v_add_f32_e32 v84, 1.0, v84
	v_rcp_f32_e32 v84, v84
	s_nop 0
	v_cndmask_b32_e64 v84, v90, v84, s[10:11]
	v_mul_f32_e32 v90, v85, v97
	v_fma_f32 v85, v85, v97, v174
	v_mul_f32_e32 v85, 0xbfb8aa3b, v85
	v_exp_f32_e32 v85, v85
	s_nop 0
	v_add_f32_e32 v85, 1.0, v85
	v_rcp_f32_e32 v85, v85
	s_nop 0
	v_cndmask_b32_e64 v85, v90, v85, s[10:11]
	v_mul_f32_e32 v90, v86, v97
	v_fma_f32 v86, v86, v97, v183
	v_mul_f32_e32 v86, 0xbfb8aa3b, v86
	v_exp_f32_e32 v86, v86
	s_nop 0
	v_add_f32_e32 v86, 1.0, v86
	v_rcp_f32_e32 v86, v86
	s_nop 0
	v_cndmask_b32_e64 v86, v90, v86, s[10:11]
	v_mul_f32_e32 v90, v87, v97
	v_fma_f32 v87, v87, v97, v178
	v_mul_f32_e32 v87, 0xbfb8aa3b, v87
	v_exp_f32_e32 v87, v87
	s_nop 0
	v_add_f32_e32 v87, 1.0, v87
	v_rcp_f32_e32 v87, v87
	s_nop 0
	v_cndmask_b32_e64 v87, v90, v87, s[10:11]
	v_mul_f32_e32 v90, v80, v97
	v_fma_f32 v80, v80, v97, v184
	v_mul_f32_e32 v80, 0xbfb8aa3b, v80
	v_exp_f32_e32 v80, v80
	s_nop 0
	v_add_f32_e32 v80, 1.0, v80
	v_rcp_f32_e32 v80, v80
	s_nop 0
	v_cndmask_b32_e64 v90, v90, v80, s[10:11]
	v_mul_f32_e32 v80, v81, v97
	v_fma_f32 v81, v81, v97, v180
	v_mul_f32_e32 v81, 0xbfb8aa3b, v81
	v_exp_f32_e32 v81, v81
	s_nop 0
	v_add_f32_e32 v81, 1.0, v81
	v_rcp_f32_e32 v81, v81
	s_nop 0
	v_cndmask_b32_e64 v91, v80, v81, s[10:11]
	v_fma_f32 v81, v82, v97, v185
	v_mul_f32_e32 v81, 0xbfb8aa3b, v81
	v_exp_f32_e32 v81, v81
	v_mul_f32_e32 v80, v82, v97
	v_cvt_pk_bf16_f32 v82, v90, v91
	v_add_f32_e32 v81, 1.0, v81
	v_rcp_f32_e32 v81, v81
	s_nop 0
	v_cndmask_b32_e64 v92, v80, v81, s[10:11]
	v_fma_f32 v81, v83, v97, v182
	v_mul_f32_e32 v81, 0xbfb8aa3b, v81
	v_exp_f32_e32 v81, v81
	v_mul_f32_e32 v80, v83, v97
	v_add_f32_e32 v81, 1.0, v81
	v_rcp_f32_e32 v81, v81
	s_nop 0
	v_cndmask_b32_e64 v83, v80, v81, s[10:11]
	v_cvt_pk_bf16_f32 v80, v84, v85
	v_cvt_pk_bf16_f32 v81, v86, v87
	v_cvt_pk_bf16_f32 v83, v92, v83
	global_store_dwordx4 v[88:89], v[80:83], off
	v_bitop3_b32 v88, v152, s6, 48 bitop3:0xc8
	s_nop 0
	v_or_b32_e32 v80, 48, v152
	v_ashrrev_i32_e32 v81, 31, v80
	v_lshl_add_u64 v[82:83], v[80:81], 2, s[44:45]
	s_nop 0
	v_lshlrev_b64 v[82:83], 13, v[80:81]
	v_or_b32_e32 v80, s17, v88
	s_cbranch_vccnz .LBB0_544
	s_and_b64 vcc, exec, s[12:13]
	s_mov_b64 s[6:7], -1
	s_cbranch_vccnz .LBB0_541
	s_andn2_b64 vcc, exec, s[90:91]
	s_cbranch_vccnz .LBB0_538
	s_andn2_b64 vcc, exec, s[88:89]
	s_cbranch_vccnz .LBB0_535
	v_lshl_add_u64 v[84:85], s[20:21], 0, v[82:83]
	v_lshl_add_u64 v[84:85], s[0:1], 1, v[84:85]
	v_lshl_add_u64 v[84:85], v[84:85], 0, v[136:137]
	v_lshl_add_u64 v[86:87], v[84:85], 0, s[30:31]
	s_mov_b64 s[6:7], 0

; __device__ __forceinline__ float rstd_of(const float* ss, int row) { return __builtin_amdgcn_rsqf(ss[row] * (1.0f / 1024.0f) + RMS_EPS); }
;     __device__ __forceinline__ void operator()(const Acc& acc, const Unit& u, int wr, int wc, int fr, int fq) const {
;     ...
;                 const int row = row0 + ai * HALF + m * 16; const float rs = rstd_of(ss, row) * sc;
;                 const int b = row >> 11, t = row & (SEQ - 1);
.LBB0_546:

; __device__ __forceinline__ unsigned cvt_pk_bf16(float lo, float hi) { f32x2_t v = {lo, hi}; bf16x2_t b = __builtin_convertvector(v, bf16x2_t); return __builtin_bit_cast(unsigned, b); }
; __device__ __forceinline__ float rstd_of(const float* ss, int row) { return __builtin_amdgcn_rsqf(ss[row] * (1.0f / 1024.0f) + RMS_EPS); }
; __device__ __forceinline__ float sigmoidf_(float v) { return __builtin_amdgcn_rcpf(1.0f + __builtin_amdgcn_exp2f(-v * LOG2E)); }
;     __device__ __forceinline__ void operator()(const Acc& acc, const Unit& u, int wr, int wc, int fr, int fq) const {
;     ...
;                 const int row = row0 + ai * HALF + m * 16; const float rs = rstd_of(ss, row) * sc;
;                 const int b = row >> 11, t = row & (SEQ - 1);
; #pragma unroll
;                 for (int bj = 0; bj < 2; ++bj) {
;                     float o[8];
; #pragma unroll
;                     for (int n = 0; n < 2; ++n)
; #pragma unroll
;                         for (int e = 0; e < 4; ++e) { float v = acc[ai][bj][m][n][e] * rs; if (isg) v = sigmoidf_(v + bv[bj][4 * n + e]); o[4 * n + e] = v; }
;                     u32x4 w; w.x = cvt_pk_bf16(o[0], o[1]); w.y = cvt_pk_bf16(o[2], o[3]); w.z = cvt_pk_bf16(o[4], o[5]); w.w = cvt_pk_bf16(o[6], o[7]);
;                     bf16_t* dst;
;                     if (tile < 4) dst = P + (size_t)row * PP + C_DQ + tile * BM + bj * HALF + cc;
;                     else if (tile < 8) dst = KD + ((size_t)((b * 8 + (tile - 4) * 2 + bj) * SEQ + t)) * 128 + cc;
;                     else if (tile < 12) dst = P + (size_t)row * PP + C_SQ + (tile - 8) * BM + bj * HALF + cc;
;                     else if (tile == 12) { const int ccf = bj * HALF + cc; dst = KS + ((size_t)((b * 4 + (ccf >> 6)) * SEQ + t)) * 64 + (ccf & 63); }
;                     else dst = P + (size_t)row * PP + C_GA + (tile - 13) * BM + bj * HALF + cc;
;                     *(u32x4*)dst = w;
	v_fmamk_f32 v81, v223, 0x3a800000, v170
	v_rsq_f32_e32 v81, v81
	s_mov_b64 s[94:95], -1
	s_and_b64 vcc, exec, s[14:15]
	v_mul_f32_e32 v81, v153, v81
	v_mul_f32_e32 v89, v76, v81
	v_fma_f32 v76, v76, v81, v187
	v_mul_f32_e32 v76, 0xbfb8aa3b, v76
	v_exp_f32_e32 v76, v76
	s_nop 0
	v_add_f32_e32 v76, 1.0, v76
	v_rcp_f32_e32 v76, v76
	s_nop 0
	v_cndmask_b32_e64 v76, v89, v76, s[10:11]
	v_mul_f32_e32 v89, v77, v81
	v_fma_f32 v77, v77, v81, v186
	v_mul_f32_e32 v77, 0xbfb8aa3b, v77
	v_exp_f32_e32 v77, v77
	s_nop 0
	v_add_f32_e32 v77, 1.0, v77
	v_rcp_f32_e32 v77, v77
	s_nop 0
	v_cndmask_b32_e64 v77, v89, v77, s[10:11]
	v_mul_f32_e32 v89, v78, v81
	v_fma_f32 v78, v78, v81, v191
	v_mul_f32_e32 v78, 0xbfb8aa3b, v78
	v_exp_f32_e32 v78, v78
	s_nop 0
	v_add_f32_e32 v78, 1.0, v78
	v_rcp_f32_e32 v78, v78
	s_nop 0
	v_cndmask_b32_e64 v78, v89, v78, s[10:11]
	v_mul_f32_e32 v89, v79, v81
	v_fma_f32 v79, v79, v81, v188
	v_mul_f32_e32 v79, 0xbfb8aa3b, v79
	v_exp_f32_e32 v79, v79
	s_nop 0
	v_add_f32_e32 v79, 1.0, v79
	v_rcp_f32_e32 v79, v79
	s_nop 0
	v_cndmask_b32_e64 v79, v89, v79, s[10:11]
	v_mul_f32_e32 v89, v72, v81
	v_fma_f32 v72, v72, v81, v192
	v_mul_f32_e32 v72, 0xbfb8aa3b, v72
	v_exp_f32_e32 v72, v72
	s_nop 0
	v_add_f32_e32 v72, 1.0, v72
	v_rcp_f32_e32 v72, v72
	s_nop 0
	v_cndmask_b32_e64 v89, v89, v72, s[10:11]
	v_mul_f32_e32 v72, v73, v81
	v_fma_f32 v73, v73, v81, v189
	v_mul_f32_e32 v73, 0xbfb8aa3b, v73
	v_exp_f32_e32 v73, v73
	s_nop 0
	v_add_f32_e32 v73, 1.0, v73
	v_rcp_f32_e32 v73, v73
	s_nop 0
	v_cndmask_b32_e64 v90, v72, v73, s[10:11]
	v_fma_f32 v73, v74, v81, v193
	v_mul_f32_e32 v73, 0xbfb8aa3b, v73
	v_exp_f32_e32 v73, v73
	v_mul_f32_e32 v72, v74, v81
	v_cvt_pk_bf16_f32 v74, v89, v90
	v_add_f32_e32 v73, 1.0, v73
	v_rcp_f32_e32 v73, v73
	s_nop 0
	v_cndmask_b32_e64 v91, v72, v73, s[10:11]
	v_fma_f32 v73, v75, v81, v190
	v_mul_f32_e32 v73, 0xbfb8aa3b, v73
	v_exp_f32_e32 v73, v73
	v_mul_f32_e32 v72, v75, v81
	v_add_f32_e32 v73, 1.0, v73
	v_rcp_f32_e32 v73, v73
	s_nop 0
	v_cndmask_b32_e64 v75, v72, v73, s[10:11]
	v_cvt_pk_bf16_f32 v72, v76, v77
	v_cvt_pk_bf16_f32 v73, v78, v79
	v_cvt_pk_bf16_f32 v75, v91, v75
	global_store_dwordx4 v[86:87], v[72:75], off
	s_cbranch_vccnz .LBB0_560
	s_and_b64 vcc, exec, s[12:13]
	s_mov_b64 s[6:7], -1
	s_cbranch_vccnz .LBB0_557
	s_andn2_b64 vcc, exec, s[90:91]
	s_cbranch_vccnz .LBB0_554
	s_andn2_b64 vcc, exec, s[88:89]
	s_cbranch_vccnz .LBB0_551
	v_lshl_add_u64 v[72:73], s[0:1], 1, v[84:85]
	v_lshl_add_u64 v[72:73], v[72:73], 0, v[136:137]
	v_lshl_add_u64 v[72:73], v[72:73], 0, s[36:37]
	s_mov_b64 s[6:7], 0

; __device__ __forceinline__ unsigned cvt_pk_bf16(float lo, float hi) { f32x2_t v = {lo, hi}; bf16x2_t b = __builtin_convertvector(v, bf16x2_t); return __builtin_bit_cast(unsigned, b); }
; __device__ __forceinline__ float rstd_of(const float* ss, int row) { return __builtin_amdgcn_rsqf(ss[row] * (1.0f / 1024.0f) + RMS_EPS); }
; __device__ __forceinline__ float sigmoidf_(float v) { return __builtin_amdgcn_rcpf(1.0f + __builtin_amdgcn_exp2f(-v * LOG2E)); }
;     __device__ __forceinline__ void operator()(const Acc& acc, const Unit& u, int wr, int wc, int fr, int fq) const {
;     ...
;                 const int row = row0 + ai * HALF + m * 16; const float rs = rstd_of(ss, row) * sc;
;                 const int b = row >> 11, t = row & (SEQ - 1);
;     ...
;                 for (int bj = 0; bj < 2; ++bj) {
;                     float o[8];
; #pragma unroll
;                     for (int n = 0; n < 2; ++n)
; #pragma unroll
;                         for (int e = 0; e < 4; ++e) { float v = acc[ai][bj][m][n][e] * rs; if (isg) v = sigmoidf_(v + bv[bj][4 * n + e]); o[4 * n + e] = v; }
;                     u32x4 w; w.x = cvt_pk_bf16(o[0], o[1]); w.y = cvt_pk_bf16(o[2], o[3]); w.z = cvt_pk_bf16(o[4], o[5]); w.w = cvt_pk_bf16(o[6], o[7]);
;                     bf16_t* dst;
;                     if (tile < 4) dst = P + (size_t)row * PP + C_DQ + tile * BM + bj * HALF + cc;
;                     else if (tile < 8) dst = KD + ((size_t)((b * 8 + (tile - 4) * 2 + bj) * SEQ + t)) * 128 + cc;
;                     else if (tile < 12) dst = P + (size_t)row * PP + C_SQ + (tile - 8) * BM + bj * HALF + cc;
;                     else if (tile == 12) { const int ccf = bj * HALF + cc; dst = KS + ((size_t)((b * 4 + (ccf >> 6)) * SEQ + t)) * 64 + (ccf & 63); }
;                     else dst = P + (size_t)row * PP + C_GA + (tile - 13) * BM + bj * HALF + cc;
;                     *(u32x4*)dst = w;
.LBB0_562:
	v_mul_f32_e32 v74, v68, v81
	v_fma_f32 v68, v68, v81, v181
	v_mul_f32_e32 v68, 0xbfb8aa3b, v68
	v_exp_f32_e32 v68, v68
	s_mov_b64 s[94:95], -1
	s_and_b64 vcc, exec, s[14:15]
	v_add_f32_e32 v68, 1.0, v68
	v_rcp_f32_e32 v68, v68
	s_nop 0
	v_cndmask_b32_e64 v68, v74, v68, s[10:11]
	v_mul_f32_e32 v74, v69, v81
	v_fma_f32 v69, v69, v81, v174
	v_mul_f32_e32 v69, 0xbfb8aa3b, v69
	v_exp_f32_e32 v69, v69
	s_nop 0
	v_add_f32_e32 v69, 1.0, v69
	v_rcp_f32_e32 v69, v69
	s_nop 0
	v_cndmask_b32_e64 v69, v74, v69, s[10:11]
	v_mul_f32_e32 v74, v70, v81
	v_fma_f32 v70, v70, v81, v183
	v_mul_f32_e32 v70, 0xbfb8aa3b, v70
	v_exp_f32_e32 v70, v70
	s_nop 0
	v_add_f32_e32 v70, 1.0, v70
	v_rcp_f32_e32 v70, v70
	s_nop 0
	v_cndmask_b32_e64 v70, v74, v70, s[10:11]
	v_mul_f32_e32 v74, v71, v81
	v_fma_f32 v71, v71, v81, v178
	v_mul_f32_e32 v71, 0xbfb8aa3b, v71
	v_exp_f32_e32 v71, v71
	s_nop 0
	v_add_f32_e32 v71, 1.0, v71
	v_rcp_f32_e32 v71, v71
	s_nop 0
	v_cndmask_b32_e64 v71, v74, v71, s[10:11]
	v_mul_f32_e32 v74, v64, v81
	v_fma_f32 v64, v64, v81, v184
	v_mul_f32_e32 v64, 0xbfb8aa3b, v64
	v_exp_f32_e32 v64, v64
	s_nop 0
	v_add_f32_e32 v64, 1.0, v64
	v_rcp_f32_e32 v64, v64
	s_nop 0
	v_cndmask_b32_e64 v74, v74, v64, s[10:11]
	v_mul_f32_e32 v64, v65, v81
	v_fma_f32 v65, v65, v81, v180
	v_mul_f32_e32 v65, 0xbfb8aa3b, v65
	v_exp_f32_e32 v65, v65
	s_nop 0
	v_add_f32_e32 v65, 1.0, v65
	v_rcp_f32_e32 v65, v65
	s_nop 0
	v_cndmask_b32_e64 v75, v64, v65, s[10:11]
	v_fma_f32 v65, v66, v81, v185
	v_mul_f32_e32 v65, 0xbfb8aa3b, v65
	v_exp_f32_e32 v65, v65
	v_mul_f32_e32 v64, v66, v81
	v_cvt_pk_bf16_f32 v66, v74, v75
	v_add_f32_e32 v65, 1.0, v65
	v_rcp_f32_e32 v65, v65
	s_nop 0
	v_cndmask_b32_e64 v76, v64, v65, s[10:11]
	v_fma_f32 v65, v67, v81, v182
	v_mul_f32_e32 v65, 0xbfb8aa3b, v65
	v_exp_f32_e32 v65, v65
	v_mul_f32_e32 v64, v67, v81
	v_add_f32_e32 v65, 1.0, v65
	v_rcp_f32_e32 v65, v65
	s_nop 0
	v_cndmask_b32_e64 v67, v64, v65, s[10:11]
	v_cvt_pk_bf16_f32 v64, v68, v69
	v_cvt_pk_bf16_f32 v65, v70, v71
	v_cvt_pk_bf16_f32 v67, v76, v67
	global_store_dwordx4 v[72:73], v[64:67], off
	s_nop 0
	s_nop 0
	v_add_u32_e32 v64, 0x80, v152
	v_ashrrev_i32_e32 v65, 11, v64
	v_lshl_or_b32 v73, v65, 13, s23
	v_lshl_add_u32 v72, v65, 3, s2
	v_ashrrev_i32_e32 v65, 31, v64
	v_and_b32_e32 v74, 0x7cf, v64
	v_lshlrev_b64 v[66:67], 13, v[64:65]
	v_or_b32_e32 v64, v73, v74
	s_cbranch_vccnz .LBB0_576
	s_and_b64 vcc, exec, s[12:13]
	s_mov_b64 s[6:7], -1
	s_cbranch_vccnz .LBB0_573
	s_andn2_b64 vcc, exec, s[90:91]
	s_cbranch_vccnz .LBB0_570
	s_andn2_b64 vcc, exec, s[88:89]
	s_cbranch_vccnz .LBB0_567
	v_lshl_add_u64 v[68:69], s[20:21], 0, v[66:67]
	v_lshl_add_u64 v[68:69], s[0:1], 1, v[68:69]
	v_lshl_add_u64 v[68:69], v[68:69], 0, v[136:137]
	v_lshl_add_u64 v[70:71], v[68:69], 0, s[30:31]
	s_mov_b64 s[6:7], 0

; __device__ __forceinline__ float rstd_of(const float* ss, int row) { return __builtin_amdgcn_rsqf(ss[row] * (1.0f / 1024.0f) + RMS_EPS); }
;     __device__ __forceinline__ void operator()(const Acc& acc, const Unit& u, int wr, int wc, int fr, int fq) const {
;     ...
;                 const int row = row0 + ai * HALF + m * 16; const float rs = rstd_of(ss, row) * sc;
;                 const int b = row >> 11, t = row & (SEQ - 1);
.LBB0_578:

; __device__ __forceinline__ unsigned cvt_pk_bf16(float lo, float hi) { f32x2_t v = {lo, hi}; bf16x2_t b = __builtin_convertvector(v, bf16x2_t); return __builtin_bit_cast(unsigned, b); }
; __device__ __forceinline__ float rstd_of(const float* ss, int row) { return __builtin_amdgcn_rsqf(ss[row] * (1.0f / 1024.0f) + RMS_EPS); }
; __device__ __forceinline__ float sigmoidf_(float v) { return __builtin_amdgcn_rcpf(1.0f + __builtin_amdgcn_exp2f(-v * LOG2E)); }
;     __device__ __forceinline__ void operator()(const Acc& acc, const Unit& u, int wr, int wc, int fr, int fq) const {
;     ...
;                 const int row = row0 + ai * HALF + m * 16; const float rs = rstd_of(ss, row) * sc;
;                 const int b = row >> 11, t = row & (SEQ - 1);
; #pragma unroll
;                 for (int bj = 0; bj < 2; ++bj) {
;                     float o[8];
; #pragma unroll
;                     for (int n = 0; n < 2; ++n)
; #pragma unroll
;                         for (int e = 0; e < 4; ++e) { float v = acc[ai][bj][m][n][e] * rs; if (isg) v = sigmoidf_(v + bv[bj][4 * n + e]); o[4 * n + e] = v; }
;                     u32x4 w; w.x = cvt_pk_bf16(o[0], o[1]); w.y = cvt_pk_bf16(o[2], o[3]); w.z = cvt_pk_bf16(o[4], o[5]); w.w = cvt_pk_bf16(o[6], o[7]);
;                     bf16_t* dst;
;                     if (tile < 4) dst = P + (size_t)row * PP + C_DQ + tile * BM + bj * HALF + cc;
;                     else if (tile < 8) dst = KD + ((size_t)((b * 8 + (tile - 4) * 2 + bj) * SEQ + t)) * 128 + cc;
;                     else if (tile < 12) dst = P + (size_t)row * PP + C_SQ + (tile - 8) * BM + bj * HALF + cc;
;                     else if (tile == 12) { const int ccf = bj * HALF + cc; dst = KS + ((size_t)((b * 4 + (ccf >> 6)) * SEQ + t)) * 64 + (ccf & 63); }
;                     else dst = P + (size_t)row * PP + C_GA + (tile - 13) * BM + bj * HALF + cc;
;                     *(u32x4*)dst = w;
	v_fmamk_f32 v65, v224, 0x3a800000, v170
	v_rsq_f32_e32 v65, v65
	s_mov_b64 s[94:95], -1
	s_and_b64 vcc, exec, s[14:15]
	v_mul_f32_e32 v65, v153, v65
	v_mul_f32_e32 v75, v60, v65
	v_fma_f32 v60, v60, v65, v187
	v_mul_f32_e32 v60, 0xbfb8aa3b, v60
	v_exp_f32_e32 v60, v60
	s_nop 0
	v_add_f32_e32 v60, 1.0, v60
	v_rcp_f32_e32 v60, v60
	s_nop 0
	v_cndmask_b32_e64 v60, v75, v60, s[10:11]
	v_mul_f32_e32 v75, v61, v65
	v_fma_f32 v61, v61, v65, v186
	v_mul_f32_e32 v61, 0xbfb8aa3b, v61
	v_exp_f32_e32 v61, v61
	s_nop 0
	v_add_f32_e32 v61, 1.0, v61
	v_rcp_f32_e32 v61, v61
	s_nop 0
	v_cndmask_b32_e64 v61, v75, v61, s[10:11]
	v_mul_f32_e32 v75, v62, v65
	v_fma_f32 v62, v62, v65, v191
	v_mul_f32_e32 v62, 0xbfb8aa3b, v62
	v_exp_f32_e32 v62, v62
	s_nop 0
	v_add_f32_e32 v62, 1.0, v62
	v_rcp_f32_e32 v62, v62
	s_nop 0
	v_cndmask_b32_e64 v62, v75, v62, s[10:11]
	v_mul_f32_e32 v75, v63, v65
	v_fma_f32 v63, v63, v65, v188
	v_mul_f32_e32 v63, 0xbfb8aa3b, v63
	v_exp_f32_e32 v63, v63
	s_nop 0
	v_add_f32_e32 v63, 1.0, v63
	v_rcp_f32_e32 v63, v63
	s_nop 0
	v_cndmask_b32_e64 v63, v75, v63, s[10:11]
	v_mul_f32_e32 v75, v56, v65
	v_fma_f32 v56, v56, v65, v192
	v_mul_f32_e32 v56, 0xbfb8aa3b, v56
	v_exp_f32_e32 v56, v56
	s_nop 0
	v_add_f32_e32 v56, 1.0, v56
	v_rcp_f32_e32 v56, v56
	s_nop 0
	v_cndmask_b32_e64 v75, v75, v56, s[10:11]
	v_mul_f32_e32 v56, v57, v65
	v_fma_f32 v57, v57, v65, v189
	v_mul_f32_e32 v57, 0xbfb8aa3b, v57
	v_exp_f32_e32 v57, v57
	s_nop 0
	v_add_f32_e32 v57, 1.0, v57
	v_rcp_f32_e32 v57, v57
	s_nop 0
	v_cndmask_b32_e64 v76, v56, v57, s[10:11]
	v_fma_f32 v57, v58, v65, v193
	v_mul_f32_e32 v57, 0xbfb8aa3b, v57
	v_exp_f32_e32 v57, v57
	v_mul_f32_e32 v56, v58, v65
	v_cvt_pk_bf16_f32 v58, v75, v76
	v_add_f32_e32 v57, 1.0, v57
	v_rcp_f32_e32 v57, v57
	s_nop 0
	v_cndmask_b32_e64 v77, v56, v57, s[10:11]
	v_fma_f32 v57, v59, v65, v190
	v_mul_f32_e32 v57, 0xbfb8aa3b, v57
	v_exp_f32_e32 v57, v57
	v_mul_f32_e32 v56, v59, v65
	v_add_f32_e32 v57, 1.0, v57
	v_rcp_f32_e32 v57, v57
	s_nop 0
	v_cndmask_b32_e64 v59, v56, v57, s[10:11]
	v_cvt_pk_bf16_f32 v56, v60, v61
	v_cvt_pk_bf16_f32 v57, v62, v63
	v_cvt_pk_bf16_f32 v59, v77, v59
	global_store_dwordx4 v[70:71], v[56:59], off
	s_cbranch_vccnz .LBB0_592
	s_and_b64 vcc, exec, s[12:13]
	s_mov_b64 s[6:7], -1
	s_cbranch_vccnz .LBB0_589
	s_andn2_b64 vcc, exec, s[90:91]
	s_cbranch_vccnz .LBB0_586
	s_andn2_b64 vcc, exec, s[88:89]
	s_cbranch_vccnz .LBB0_583
	v_lshl_add_u64 v[56:57], s[0:1], 1, v[68:69]
	v_lshl_add_u64 v[56:57], v[56:57], 0, v[136:137]
	v_lshl_add_u64 v[56:57], v[56:57], 0, s[36:37]
	s_mov_b64 s[6:7], 0

; __device__ __forceinline__ unsigned cvt_pk_bf16(float lo, float hi) { f32x2_t v = {lo, hi}; bf16x2_t b = __builtin_convertvector(v, bf16x2_t); return __builtin_bit_cast(unsigned, b); }
; __device__ __forceinline__ float rstd_of(const float* ss, int row) { return __builtin_amdgcn_rsqf(ss[row] * (1.0f / 1024.0f) + RMS_EPS); }
; __device__ __forceinline__ float sigmoidf_(float v) { return __builtin_amdgcn_rcpf(1.0f + __builtin_amdgcn_exp2f(-v * LOG2E)); }
;     __device__ __forceinline__ void operator()(const Acc& acc, const Unit& u, int wr, int wc, int fr, int fq) const {
;     ...
;                 const int row = row0 + ai * HALF + m * 16; const float rs = rstd_of(ss, row) * sc;
;                 const int b = row >> 11, t = row & (SEQ - 1);
;     ...
;                 for (int bj = 0; bj < 2; ++bj) {
;                     float o[8];
; #pragma unroll
;                     for (int n = 0; n < 2; ++n)
; #pragma unroll
;                         for (int e = 0; e < 4; ++e) { float v = acc[ai][bj][m][n][e] * rs; if (isg) v = sigmoidf_(v + bv[bj][4 * n + e]); o[4 * n + e] = v; }
;                     u32x4 w; w.x = cvt_pk_bf16(o[0], o[1]); w.y = cvt_pk_bf16(o[2], o[3]); w.z = cvt_pk_bf16(o[4], o[5]); w.w = cvt_pk_bf16(o[6], o[7]);
;                     bf16_t* dst;
;                     if (tile < 4) dst = P + (size_t)row * PP + C_DQ + tile * BM + bj * HALF + cc;
;                     else if (tile < 8) dst = KD + ((size_t)((b * 8 + (tile - 4) * 2 + bj) * SEQ + t)) * 128 + cc;
;                     else if (tile < 12) dst = P + (size_t)row * PP + C_SQ + (tile - 8) * BM + bj * HALF + cc;
;                     else if (tile == 12) { const int ccf = bj * HALF + cc; dst = KS + ((size_t)((b * 4 + (ccf >> 6)) * SEQ + t)) * 64 + (ccf & 63); }
;                     else dst = P + (size_t)row * PP + C_GA + (tile - 13) * BM + bj * HALF + cc;
;                     *(u32x4*)dst = w;
.LBB0_594:
	v_mul_f32_e32 v58, v52, v65
	v_fma_f32 v52, v52, v65, v181
	v_mul_f32_e32 v52, 0xbfb8aa3b, v52
	v_exp_f32_e32 v52, v52
	s_mov_b64 s[94:95], -1
	s_and_b64 vcc, exec, s[14:15]
	v_add_f32_e32 v52, 1.0, v52
	v_rcp_f32_e32 v52, v52
	s_nop 0
	v_cndmask_b32_e64 v52, v58, v52, s[10:11]
	v_mul_f32_e32 v58, v53, v65
	v_fma_f32 v53, v53, v65, v174
	v_mul_f32_e32 v53, 0xbfb8aa3b, v53
	v_exp_f32_e32 v53, v53
	s_nop 0
	v_add_f32_e32 v53, 1.0, v53
	v_rcp_f32_e32 v53, v53
	s_nop 0
	v_cndmask_b32_e64 v53, v58, v53, s[10:11]
	v_mul_f32_e32 v58, v54, v65
	v_fma_f32 v54, v54, v65, v183
	v_mul_f32_e32 v54, 0xbfb8aa3b, v54
	v_exp_f32_e32 v54, v54
	s_nop 0
	v_add_f32_e32 v54, 1.0, v54
	v_rcp_f32_e32 v54, v54
	s_nop 0
	v_cndmask_b32_e64 v54, v58, v54, s[10:11]
	v_mul_f32_e32 v58, v55, v65
	v_fma_f32 v55, v55, v65, v178
	v_mul_f32_e32 v55, 0xbfb8aa3b, v55
	v_exp_f32_e32 v55, v55
	s_nop 0
	v_add_f32_e32 v55, 1.0, v55
	v_rcp_f32_e32 v55, v55
	s_nop 0
	v_cndmask_b32_e64 v55, v58, v55, s[10:11]
	v_mul_f32_e32 v58, v48, v65
	v_fma_f32 v48, v48, v65, v184
	v_mul_f32_e32 v48, 0xbfb8aa3b, v48
	v_exp_f32_e32 v48, v48
	s_nop 0
	v_add_f32_e32 v48, 1.0, v48
	v_rcp_f32_e32 v48, v48
	s_nop 0
	v_cndmask_b32_e64 v58, v58, v48, s[10:11]
	v_mul_f32_e32 v48, v49, v65
	v_fma_f32 v49, v49, v65, v180
	v_mul_f32_e32 v49, 0xbfb8aa3b, v49
	v_exp_f32_e32 v49, v49
	s_nop 0
	v_add_f32_e32 v49, 1.0, v49
	v_rcp_f32_e32 v49, v49
	s_nop 0
	v_cndmask_b32_e64 v59, v48, v49, s[10:11]
	v_fma_f32 v49, v50, v65, v185
	v_mul_f32_e32 v49, 0xbfb8aa3b, v49
	v_exp_f32_e32 v49, v49
	v_mul_f32_e32 v48, v50, v65
	v_cvt_pk_bf16_f32 v50, v58, v59
	v_add_f32_e32 v49, 1.0, v49
	v_rcp_f32_e32 v49, v49
	s_nop 0
	v_cndmask_b32_e64 v60, v48, v49, s[10:11]
	v_fma_f32 v49, v51, v65, v182
	v_mul_f32_e32 v49, 0xbfb8aa3b, v49
	v_exp_f32_e32 v49, v49
	v_mul_f32_e32 v48, v51, v65
	v_add_f32_e32 v49, 1.0, v49
	v_rcp_f32_e32 v49, v49
	s_nop 0
	v_cndmask_b32_e64 v51, v48, v49, s[10:11]
	v_cvt_pk_bf16_f32 v48, v52, v53
	v_cvt_pk_bf16_f32 v49, v54, v55
	v_cvt_pk_bf16_f32 v51, v60, v51
	global_store_dwordx4 v[56:57], v[48:51], off
	s_nop 0
	s_nop 0
	v_add_u32_e32 v48, 0x90, v152
	v_ashrrev_i32_e32 v49, 31, v48
	v_and_b32_e32 v56, 0x7df, v48
	v_lshlrev_b64 v[50:51], 13, v[48:49]
	v_or_b32_e32 v48, v73, v56
	s_cbranch_vccnz .LBB0_608
	s_and_b64 vcc, exec, s[12:13]
	s_mov_b64 s[6:7], -1
	s_cbranch_vccnz .LBB0_605
	s_andn2_b64 vcc, exec, s[90:91]
	s_cbranch_vccnz .LBB0_602
	s_andn2_b64 vcc, exec, s[88:89]
	s_cbranch_vccnz .LBB0_599
	v_lshl_add_u64 v[52:53], s[20:21], 0, v[50:51]
	v_lshl_add_u64 v[52:53], s[0:1], 1, v[52:53]
	v_lshl_add_u64 v[52:53], v[52:53], 0, v[136:137]
	v_lshl_add_u64 v[54:55], v[52:53], 0, s[30:31]
	s_mov_b64 s[6:7], 0

; __device__ __forceinline__ float rstd_of(const float* ss, int row) { return __builtin_amdgcn_rsqf(ss[row] * (1.0f / 1024.0f) + RMS_EPS); }
;     __device__ __forceinline__ void operator()(const Acc& acc, const Unit& u, int wr, int wc, int fr, int fq) const {
;     ...
;                 const int row = row0 + ai * HALF + m * 16; const float rs = rstd_of(ss, row) * sc;
;                 const int b = row >> 11, t = row & (SEQ - 1);
.LBB0_610:

; __device__ __forceinline__ unsigned cvt_pk_bf16(float lo, float hi) { f32x2_t v = {lo, hi}; bf16x2_t b = __builtin_convertvector(v, bf16x2_t); return __builtin_bit_cast(unsigned, b); }
; __device__ __forceinline__ float rstd_of(const float* ss, int row) { return __builtin_amdgcn_rsqf(ss[row] * (1.0f / 1024.0f) + RMS_EPS); }
; __device__ __forceinline__ float sigmoidf_(float v) { return __builtin_amdgcn_rcpf(1.0f + __builtin_amdgcn_exp2f(-v * LOG2E)); }
;     __device__ __forceinline__ void operator()(const Acc& acc, const Unit& u, int wr, int wc, int fr, int fq) const {
;     ...
;                 const int row = row0 + ai * HALF + m * 16; const float rs = rstd_of(ss, row) * sc;
;                 const int b = row >> 11, t = row & (SEQ - 1);
; #pragma unroll
;                 for (int bj = 0; bj < 2; ++bj) {
;                     float o[8];
; #pragma unroll
;                     for (int n = 0; n < 2; ++n)
; #pragma unroll
;                         for (int e = 0; e < 4; ++e) { float v = acc[ai][bj][m][n][e] * rs; if (isg) v = sigmoidf_(v + bv[bj][4 * n + e]); o[4 * n + e] = v; }
;                     u32x4 w; w.x = cvt_pk_bf16(o[0], o[1]); w.y = cvt_pk_bf16(o[2], o[3]); w.z = cvt_pk_bf16(o[4], o[5]); w.w = cvt_pk_bf16(o[6], o[7]);
;                     bf16_t* dst;
;                     if (tile < 4) dst = P + (size_t)row * PP + C_DQ + tile * BM + bj * HALF + cc;
;                     else if (tile < 8) dst = KD + ((size_t)((b * 8 + (tile - 4) * 2 + bj) * SEQ + t)) * 128 + cc;
;                     else if (tile < 12) dst = P + (size_t)row * PP + C_SQ + (tile - 8) * BM + bj * HALF + cc;
;                     else if (tile == 12) { const int ccf = bj * HALF + cc; dst = KS + ((size_t)((b * 4 + (ccf >> 6)) * SEQ + t)) * 64 + (ccf & 63); }
;                     else dst = P + (size_t)row * PP + C_GA + (tile - 13) * BM + bj * HALF + cc;
;                     *(u32x4*)dst = w;
	v_fmamk_f32 v49, v225, 0x3a800000, v170
	v_rsq_f32_e32 v49, v49
	s_mov_b64 s[94:95], -1
	s_and_b64 vcc, exec, s[14:15]
	v_mul_f32_e32 v49, v153, v49
	v_mul_f32_e32 v57, v44, v49
	v_fma_f32 v44, v44, v49, v187
	v_mul_f32_e32 v44, 0xbfb8aa3b, v44
	v_exp_f32_e32 v44, v44
	s_nop 0
	v_add_f32_e32 v44, 1.0, v44
	v_rcp_f32_e32 v44, v44
	s_nop 0
	v_cndmask_b32_e64 v44, v57, v44, s[10:11]
	v_mul_f32_e32 v57, v45, v49
	v_fma_f32 v45, v45, v49, v186
	v_mul_f32_e32 v45, 0xbfb8aa3b, v45
	v_exp_f32_e32 v45, v45
	s_nop 0
	v_add_f32_e32 v45, 1.0, v45
	v_rcp_f32_e32 v45, v45
	s_nop 0
	v_cndmask_b32_e64 v45, v57, v45, s[10:11]
	v_mul_f32_e32 v57, v46, v49
	v_fma_f32 v46, v46, v49, v191
	v_mul_f32_e32 v46, 0xbfb8aa3b, v46
	v_exp_f32_e32 v46, v46
	s_nop 0
	v_add_f32_e32 v46, 1.0, v46
	v_rcp_f32_e32 v46, v46
	s_nop 0
	v_cndmask_b32_e64 v46, v57, v46, s[10:11]
	v_mul_f32_e32 v57, v47, v49
	v_fma_f32 v47, v47, v49, v188
	v_mul_f32_e32 v47, 0xbfb8aa3b, v47
	v_exp_f32_e32 v47, v47
	s_nop 0
	v_add_f32_e32 v47, 1.0, v47
	v_rcp_f32_e32 v47, v47
	s_nop 0
	v_cndmask_b32_e64 v47, v57, v47, s[10:11]
	v_mul_f32_e32 v57, v40, v49
	v_fma_f32 v40, v40, v49, v192
	v_mul_f32_e32 v40, 0xbfb8aa3b, v40
	v_exp_f32_e32 v40, v40
	s_nop 0
	v_add_f32_e32 v40, 1.0, v40
	v_rcp_f32_e32 v40, v40
	s_nop 0
	v_cndmask_b32_e64 v57, v57, v40, s[10:11]
	v_mul_f32_e32 v40, v41, v49
	v_fma_f32 v41, v41, v49, v189
	v_mul_f32_e32 v41, 0xbfb8aa3b, v41
	v_exp_f32_e32 v41, v41
	s_nop 0
	v_add_f32_e32 v41, 1.0, v41
	v_rcp_f32_e32 v41, v41
	s_nop 0
	v_cndmask_b32_e64 v58, v40, v41, s[10:11]
	v_fma_f32 v41, v42, v49, v193
	v_mul_f32_e32 v41, 0xbfb8aa3b, v41
	v_exp_f32_e32 v41, v41
	v_mul_f32_e32 v40, v42, v49
	v_cvt_pk_bf16_f32 v42, v57, v58
	v_add_f32_e32 v41, 1.0, v41
	v_rcp_f32_e32 v41, v41
	s_nop 0
	v_cndmask_b32_e64 v59, v40, v41, s[10:11]
	v_fma_f32 v41, v43, v49, v190
	v_mul_f32_e32 v41, 0xbfb8aa3b, v41
	v_exp_f32_e32 v41, v41
	v_mul_f32_e32 v40, v43, v49
	v_add_f32_e32 v41, 1.0, v41
	v_rcp_f32_e32 v41, v41
	s_nop 0
	v_cndmask_b32_e64 v43, v40, v41, s[10:11]
	v_cvt_pk_bf16_f32 v40, v44, v45
	v_cvt_pk_bf16_f32 v41, v46, v47
	v_cvt_pk_bf16_f32 v43, v59, v43
	global_store_dwordx4 v[54:55], v[40:43], off
	s_cbranch_vccnz .LBB0_624
	s_and_b64 vcc, exec, s[12:13]
	s_mov_b64 s[6:7], -1
	s_cbranch_vccnz .LBB0_621
	s_andn2_b64 vcc, exec, s[90:91]
	s_cbranch_vccnz .LBB0_618
	s_andn2_b64 vcc, exec, s[88:89]
	s_cbranch_vccnz .LBB0_615
	v_lshl_add_u64 v[40:41], s[0:1], 1, v[52:53]
	v_lshl_add_u64 v[40:41], v[40:41], 0, v[136:137]
	v_lshl_add_u64 v[40:41], v[40:41], 0, s[36:37]
	s_mov_b64 s[6:7], 0

; __device__ __forceinline__ unsigned cvt_pk_bf16(float lo, float hi) { f32x2_t v = {lo, hi}; bf16x2_t b = __builtin_convertvector(v, bf16x2_t); return __builtin_bit_cast(unsigned, b); }
; __device__ __forceinline__ float rstd_of(const float* ss, int row) { return __builtin_amdgcn_rsqf(ss[row] * (1.0f / 1024.0f) + RMS_EPS); }
; __device__ __forceinline__ float sigmoidf_(float v) { return __builtin_amdgcn_rcpf(1.0f + __builtin_amdgcn_exp2f(-v * LOG2E)); }
;     __device__ __forceinline__ void operator()(const Acc& acc, const Unit& u, int wr, int wc, int fr, int fq) const {
;     ...
;                 const int row = row0 + ai * HALF + m * 16; const float rs = rstd_of(ss, row) * sc;
;                 const int b = row >> 11, t = row & (SEQ - 1);
;     ...
;                 for (int bj = 0; bj < 2; ++bj) {
;                     float o[8];
; #pragma unroll
;                     for (int n = 0; n < 2; ++n)
; #pragma unroll
;                         for (int e = 0; e < 4; ++e) { float v = acc[ai][bj][m][n][e] * rs; if (isg) v = sigmoidf_(v + bv[bj][4 * n + e]); o[4 * n + e] = v; }
;                     u32x4 w; w.x = cvt_pk_bf16(o[0], o[1]); w.y = cvt_pk_bf16(o[2], o[3]); w.z = cvt_pk_bf16(o[4], o[5]); w.w = cvt_pk_bf16(o[6], o[7]);
;                     bf16_t* dst;
;                     if (tile < 4) dst = P + (size_t)row * PP + C_DQ + tile * BM + bj * HALF + cc;
;                     else if (tile < 8) dst = KD + ((size_t)((b * 8 + (tile - 4) * 2 + bj) * SEQ + t)) * 128 + cc;
;                     else if (tile < 12) dst = P + (size_t)row * PP + C_SQ + (tile - 8) * BM + bj * HALF + cc;
;                     else if (tile == 12) { const int ccf = bj * HALF + cc; dst = KS + ((size_t)((b * 4 + (ccf >> 6)) * SEQ + t)) * 64 + (ccf & 63); }
;                     else dst = P + (size_t)row * PP + C_GA + (tile - 13) * BM + bj * HALF + cc;
;                     *(u32x4*)dst = w;
.LBB0_626:
	v_mul_f32_e32 v42, v36, v49
	v_fma_f32 v36, v36, v49, v181
	v_mul_f32_e32 v36, 0xbfb8aa3b, v36
	v_exp_f32_e32 v36, v36
	s_mov_b64 s[94:95], -1
	s_and_b64 vcc, exec, s[14:15]
	v_add_f32_e32 v36, 1.0, v36
	v_rcp_f32_e32 v36, v36
	s_nop 0
	v_cndmask_b32_e64 v36, v42, v36, s[10:11]
	v_mul_f32_e32 v42, v37, v49
	v_fma_f32 v37, v37, v49, v174
	v_mul_f32_e32 v37, 0xbfb8aa3b, v37
	v_exp_f32_e32 v37, v37
	s_nop 0
	v_add_f32_e32 v37, 1.0, v37
	v_rcp_f32_e32 v37, v37
	s_nop 0
	v_cndmask_b32_e64 v37, v42, v37, s[10:11]
	v_mul_f32_e32 v42, v38, v49
	v_fma_f32 v38, v38, v49, v183
	v_mul_f32_e32 v38, 0xbfb8aa3b, v38
	v_exp_f32_e32 v38, v38
	s_nop 0
	v_add_f32_e32 v38, 1.0, v38
	v_rcp_f32_e32 v38, v38
	s_nop 0
	v_cndmask_b32_e64 v38, v42, v38, s[10:11]
	v_mul_f32_e32 v42, v39, v49
	v_fma_f32 v39, v39, v49, v178
	v_mul_f32_e32 v39, 0xbfb8aa3b, v39
	v_exp_f32_e32 v39, v39
	s_nop 0
	v_add_f32_e32 v39, 1.0, v39
	v_rcp_f32_e32 v39, v39
	s_nop 0
	v_cndmask_b32_e64 v39, v42, v39, s[10:11]
	v_mul_f32_e32 v42, v32, v49
	v_fma_f32 v32, v32, v49, v184
	v_mul_f32_e32 v32, 0xbfb8aa3b, v32
	v_exp_f32_e32 v32, v32
	s_nop 0
	v_add_f32_e32 v32, 1.0, v32
	v_rcp_f32_e32 v32, v32
	s_nop 0
	v_cndmask_b32_e64 v42, v42, v32, s[10:11]
	v_mul_f32_e32 v32, v33, v49
	v_fma_f32 v33, v33, v49, v180
	v_mul_f32_e32 v33, 0xbfb8aa3b, v33
	v_exp_f32_e32 v33, v33
	s_nop 0
	v_add_f32_e32 v33, 1.0, v33
	v_rcp_f32_e32 v33, v33
	s_nop 0
	v_cndmask_b32_e64 v43, v32, v33, s[10:11]
	v_fma_f32 v33, v34, v49, v185
	v_mul_f32_e32 v33, 0xbfb8aa3b, v33
	v_exp_f32_e32 v33, v33
	v_mul_f32_e32 v32, v34, v49
	v_cvt_pk_bf16_f32 v34, v42, v43
	v_add_f32_e32 v33, 1.0, v33
	v_rcp_f32_e32 v33, v33
	s_nop 0
	v_cndmask_b32_e64 v44, v32, v33, s[10:11]
	v_fma_f32 v33, v35, v49, v182
	v_mul_f32_e32 v33, 0xbfb8aa3b, v33
	v_exp_f32_e32 v33, v33
	v_mul_f32_e32 v32, v35, v49
	v_add_f32_e32 v33, 1.0, v33
	v_rcp_f32_e32 v33, v33
	s_nop 0
	v_cndmask_b32_e64 v35, v32, v33, s[10:11]
	v_cvt_pk_bf16_f32 v32, v36, v37
	v_cvt_pk_bf16_f32 v33, v38, v39
	v_cvt_pk_bf16_f32 v35, v44, v35
	global_store_dwordx4 v[40:41], v[32:35], off
	s_nop 0
	s_nop 0
	v_add_u32_e32 v32, 0xa0, v152
	v_ashrrev_i32_e32 v33, 31, v32
	v_and_b32_e32 v40, 0x7ef, v32
	v_lshlrev_b64 v[34:35], 13, v[32:33]
	v_or_b32_e32 v32, v73, v40
	s_cbranch_vccnz .LBB0_640
	s_and_b64 vcc, exec, s[12:13]
	s_mov_b64 s[6:7], -1
	s_cbranch_vccnz .LBB0_637
	s_andn2_b64 vcc, exec, s[90:91]
	s_cbranch_vccnz .LBB0_634
	s_andn2_b64 vcc, exec, s[88:89]
	s_cbranch_vccnz .LBB0_631
	v_lshl_add_u64 v[36:37], s[20:21], 0, v[34:35]
	v_lshl_add_u64 v[36:37], s[0:1], 1, v[36:37]
	v_lshl_add_u64 v[36:37], v[36:37], 0, v[136:137]
	v_lshl_add_u64 v[38:39], v[36:37], 0, s[30:31]
	s_mov_b64 s[6:7], 0

; __device__ __forceinline__ float rstd_of(const float* ss, int row) { return __builtin_amdgcn_rsqf(ss[row] * (1.0f / 1024.0f) + RMS_EPS); }
;     __device__ __forceinline__ void operator()(const Acc& acc, const Unit& u, int wr, int wc, int fr, int fq) const {
;     ...
;                 const int row = row0 + ai * HALF + m * 16; const float rs = rstd_of(ss, row) * sc;
;                 const int b = row >> 11, t = row & (SEQ - 1);
.LBB0_642:

; __device__ __forceinline__ unsigned cvt_pk_bf16(float lo, float hi) { f32x2_t v = {lo, hi}; bf16x2_t b = __builtin_convertvector(v, bf16x2_t); return __builtin_bit_cast(unsigned, b); }
; __device__ __forceinline__ float rstd_of(const float* ss, int row) { return __builtin_amdgcn_rsqf(ss[row] * (1.0f / 1024.0f) + RMS_EPS); }
; __device__ __forceinline__ float sigmoidf_(float v) { return __builtin_amdgcn_rcpf(1.0f + __builtin_amdgcn_exp2f(-v * LOG2E)); }
;     __device__ __forceinline__ void operator()(const Acc& acc, const Unit& u, int wr, int wc, int fr, int fq) const {
;     ...
;                 const int row = row0 + ai * HALF + m * 16; const float rs = rstd_of(ss, row) * sc;
;                 const int b = row >> 11, t = row & (SEQ - 1);
; #pragma unroll
;                 for (int bj = 0; bj < 2; ++bj) {
;                     float o[8];
; #pragma unroll
;                     for (int n = 0; n < 2; ++n)
; #pragma unroll
;                         for (int e = 0; e < 4; ++e) { float v = acc[ai][bj][m][n][e] * rs; if (isg) v = sigmoidf_(v + bv[bj][4 * n + e]); o[4 * n + e] = v; }
;                     u32x4 w; w.x = cvt_pk_bf16(o[0], o[1]); w.y = cvt_pk_bf16(o[2], o[3]); w.z = cvt_pk_bf16(o[4], o[5]); w.w = cvt_pk_bf16(o[6], o[7]);
;                     bf16_t* dst;
;                     if (tile < 4) dst = P + (size_t)row * PP + C_DQ + tile * BM + bj * HALF + cc;
;                     else if (tile < 8) dst = KD + ((size_t)((b * 8 + (tile - 4) * 2 + bj) * SEQ + t)) * 128 + cc;
;                     else if (tile < 12) dst = P + (size_t)row * PP + C_SQ + (tile - 8) * BM + bj * HALF + cc;
;                     else if (tile == 12) { const int ccf = bj * HALF + cc; dst = KS + ((size_t)((b * 4 + (ccf >> 6)) * SEQ + t)) * 64 + (ccf & 63); }
;                     else dst = P + (size_t)row * PP + C_GA + (tile - 13) * BM + bj * HALF + cc;
;                     *(u32x4*)dst = w;
	v_fmamk_f32 v33, v226, 0x3a800000, v170
	v_rsq_f32_e32 v33, v33
	s_mov_b64 s[94:95], -1
	s_and_b64 vcc, exec, s[14:15]
	v_mul_f32_e32 v33, v153, v33
	v_mul_f32_e32 v41, v28, v33
	v_fma_f32 v28, v28, v33, v187
	v_mul_f32_e32 v28, 0xbfb8aa3b, v28
	v_exp_f32_e32 v28, v28
	s_nop 0
	v_add_f32_e32 v28, 1.0, v28
	v_rcp_f32_e32 v28, v28
	s_nop 0
	v_cndmask_b32_e64 v28, v41, v28, s[10:11]
	v_mul_f32_e32 v41, v29, v33
	v_fma_f32 v29, v29, v33, v186
	v_mul_f32_e32 v29, 0xbfb8aa3b, v29
	v_exp_f32_e32 v29, v29
	s_nop 0
	v_add_f32_e32 v29, 1.0, v29
	v_rcp_f32_e32 v29, v29
	s_nop 0
	v_cndmask_b32_e64 v29, v41, v29, s[10:11]
	v_mul_f32_e32 v41, v30, v33
	v_fma_f32 v30, v30, v33, v191
	v_mul_f32_e32 v30, 0xbfb8aa3b, v30
	v_exp_f32_e32 v30, v30
	s_nop 0
	v_add_f32_e32 v30, 1.0, v30
	v_rcp_f32_e32 v30, v30
	s_nop 0
	v_cndmask_b32_e64 v30, v41, v30, s[10:11]
	v_mul_f32_e32 v41, v31, v33
	v_fma_f32 v31, v31, v33, v188
	v_mul_f32_e32 v31, 0xbfb8aa3b, v31
	v_exp_f32_e32 v31, v31
	s_nop 0
	v_add_f32_e32 v31, 1.0, v31
	v_rcp_f32_e32 v31, v31
	s_nop 0
	v_cndmask_b32_e64 v31, v41, v31, s[10:11]
	v_mul_f32_e32 v41, v24, v33
	v_fma_f32 v24, v24, v33, v192
	v_mul_f32_e32 v24, 0xbfb8aa3b, v24
	v_exp_f32_e32 v24, v24
	s_nop 0
	v_add_f32_e32 v24, 1.0, v24
	v_rcp_f32_e32 v24, v24
	s_nop 0
	v_cndmask_b32_e64 v41, v41, v24, s[10:11]
	v_mul_f32_e32 v24, v25, v33
	v_fma_f32 v25, v25, v33, v189
	v_mul_f32_e32 v25, 0xbfb8aa3b, v25
	v_exp_f32_e32 v25, v25
	s_nop 0
	v_add_f32_e32 v25, 1.0, v25
	v_rcp_f32_e32 v25, v25
	s_nop 0
	v_cndmask_b32_e64 v42, v24, v25, s[10:11]
	v_fma_f32 v25, v26, v33, v193
	v_mul_f32_e32 v25, 0xbfb8aa3b, v25
	v_exp_f32_e32 v25, v25
	v_mul_f32_e32 v24, v26, v33
	v_cvt_pk_bf16_f32 v26, v41, v42
	v_add_f32_e32 v25, 1.0, v25
	v_rcp_f32_e32 v25, v25
	s_nop 0
	v_cndmask_b32_e64 v43, v24, v25, s[10:11]
	v_fma_f32 v25, v27, v33, v190
	v_mul_f32_e32 v25, 0xbfb8aa3b, v25
	v_exp_f32_e32 v25, v25
	v_mul_f32_e32 v24, v27, v33
	v_add_f32_e32 v25, 1.0, v25
	v_rcp_f32_e32 v25, v25
	s_nop 0
	v_cndmask_b32_e64 v27, v24, v25, s[10:11]
	v_cvt_pk_bf16_f32 v24, v28, v29
	v_cvt_pk_bf16_f32 v25, v30, v31
	v_cvt_pk_bf16_f32 v27, v43, v27
	global_store_dwordx4 v[38:39], v[24:27], off
	s_cbranch_vccnz .LBB0_656
	s_and_b64 vcc, exec, s[12:13]
	s_mov_b64 s[6:7], -1
	s_cbranch_vccnz .LBB0_653
	s_andn2_b64 vcc, exec, s[90:91]
	s_cbranch_vccnz .LBB0_650
	s_andn2_b64 vcc, exec, s[88:89]
	s_cbranch_vccnz .LBB0_647
	v_lshl_add_u64 v[24:25], s[0:1], 1, v[36:37]
	v_lshl_add_u64 v[24:25], v[24:25], 0, v[136:137]
	v_lshl_add_u64 v[24:25], v[24:25], 0, s[36:37]
	s_mov_b64 s[6:7], 0

; __device__ __forceinline__ unsigned cvt_pk_bf16(float lo, float hi) { f32x2_t v = {lo, hi}; bf16x2_t b = __builtin_convertvector(v, bf16x2_t); return __builtin_bit_cast(unsigned, b); }
; __device__ __forceinline__ float rstd_of(const float* ss, int row) { return __builtin_amdgcn_rsqf(ss[row] * (1.0f / 1024.0f) + RMS_EPS); }
; __device__ __forceinline__ float sigmoidf_(float v) { return __builtin_amdgcn_rcpf(1.0f + __builtin_amdgcn_exp2f(-v * LOG2E)); }
;     __device__ __forceinline__ void operator()(const Acc& acc, const Unit& u, int wr, int wc, int fr, int fq) const {
;     ...
;                 const int row = row0 + ai * HALF + m * 16; const float rs = rstd_of(ss, row) * sc;
;                 const int b = row >> 11, t = row & (SEQ - 1);
;     ...
;                 for (int bj = 0; bj < 2; ++bj) {
;                     float o[8];
; #pragma unroll
;                     for (int n = 0; n < 2; ++n)
; #pragma unroll
;                         for (int e = 0; e < 4; ++e) { float v = acc[ai][bj][m][n][e] * rs; if (isg) v = sigmoidf_(v + bv[bj][4 * n + e]); o[4 * n + e] = v; }
;                     u32x4 w; w.x = cvt_pk_bf16(o[0], o[1]); w.y = cvt_pk_bf16(o[2], o[3]); w.z = cvt_pk_bf16(o[4], o[5]); w.w = cvt_pk_bf16(o[6], o[7]);
;                     bf16_t* dst;
;                     if (tile < 4) dst = P + (size_t)row * PP + C_DQ + tile * BM + bj * HALF + cc;
;                     else if (tile < 8) dst = KD + ((size_t)((b * 8 + (tile - 4) * 2 + bj) * SEQ + t)) * 128 + cc;
;                     else if (tile < 12) dst = P + (size_t)row * PP + C_SQ + (tile - 8) * BM + bj * HALF + cc;
;                     else if (tile == 12) { const int ccf = bj * HALF + cc; dst = KS + ((size_t)((b * 4 + (ccf >> 6)) * SEQ + t)) * 64 + (ccf & 63); }
;                     else dst = P + (size_t)row * PP + C_GA + (tile - 13) * BM + bj * HALF + cc;
;                     *(u32x4*)dst = w;
.LBB0_658:
	v_mul_f32_e32 v26, v20, v33
	v_fma_f32 v20, v20, v33, v181
	v_mul_f32_e32 v20, 0xbfb8aa3b, v20
	v_exp_f32_e32 v20, v20
	s_mov_b64 s[94:95], -1
	s_and_b64 vcc, exec, s[14:15]
	v_add_f32_e32 v20, 1.0, v20
	v_rcp_f32_e32 v20, v20
	s_nop 0
	v_cndmask_b32_e64 v20, v26, v20, s[10:11]
	v_mul_f32_e32 v26, v21, v33
	v_fma_f32 v21, v21, v33, v174
	v_mul_f32_e32 v21, 0xbfb8aa3b, v21
	v_exp_f32_e32 v21, v21
	s_nop 0
	v_add_f32_e32 v21, 1.0, v21
	v_rcp_f32_e32 v21, v21
	s_nop 0
	v_cndmask_b32_e64 v21, v26, v21, s[10:11]
	v_mul_f32_e32 v26, v22, v33
	v_fma_f32 v22, v22, v33, v183
	v_mul_f32_e32 v22, 0xbfb8aa3b, v22
	v_exp_f32_e32 v22, v22
	s_nop 0
	v_add_f32_e32 v22, 1.0, v22
	v_rcp_f32_e32 v22, v22
	s_nop 0
	v_cndmask_b32_e64 v22, v26, v22, s[10:11]
	v_mul_f32_e32 v26, v23, v33
	v_fma_f32 v23, v23, v33, v178
	v_mul_f32_e32 v23, 0xbfb8aa3b, v23
	v_exp_f32_e32 v23, v23
	s_nop 0
	v_add_f32_e32 v23, 1.0, v23
	v_rcp_f32_e32 v23, v23
	s_nop 0
	v_cndmask_b32_e64 v23, v26, v23, s[10:11]
	v_mul_f32_e32 v26, v16, v33
	v_fma_f32 v16, v16, v33, v184
	v_mul_f32_e32 v16, 0xbfb8aa3b, v16
	v_exp_f32_e32 v16, v16
	s_nop 0
	v_add_f32_e32 v16, 1.0, v16
	v_rcp_f32_e32 v16, v16
	s_nop 0
	v_cndmask_b32_e64 v26, v26, v16, s[10:11]
	v_mul_f32_e32 v16, v17, v33
	v_fma_f32 v17, v17, v33, v180
	v_mul_f32_e32 v17, 0xbfb8aa3b, v17
	v_exp_f32_e32 v17, v17
	s_nop 0
	v_add_f32_e32 v17, 1.0, v17
	v_rcp_f32_e32 v17, v17
	s_nop 0
	v_cndmask_b32_e64 v27, v16, v17, s[10:11]
	v_fma_f32 v17, v18, v33, v185
	v_mul_f32_e32 v17, 0xbfb8aa3b, v17
	v_exp_f32_e32 v17, v17
	v_mul_f32_e32 v16, v18, v33
	v_cvt_pk_bf16_f32 v18, v26, v27
	v_add_f32_e32 v17, 1.0, v17
	v_rcp_f32_e32 v17, v17
	s_nop 0
	v_cndmask_b32_e64 v28, v16, v17, s[10:11]
	v_fma_f32 v17, v19, v33, v182
	v_mul_f32_e32 v17, 0xbfb8aa3b, v17
	v_exp_f32_e32 v17, v17
	v_mul_f32_e32 v16, v19, v33
	v_add_f32_e32 v17, 1.0, v17
	v_rcp_f32_e32 v17, v17
	s_nop 0
	v_cndmask_b32_e64 v19, v16, v17, s[10:11]
	v_cvt_pk_bf16_f32 v16, v20, v21
	v_cvt_pk_bf16_f32 v17, v22, v23
	v_cvt_pk_bf16_f32 v19, v28, v19
	global_store_dwordx4 v[24:25], v[16:19], off
	s_nop 0
	s_nop 0
	v_add_u32_e32 v16, 0xb0, v152
	v_ashrrev_i32_e32 v17, 31, v16
	v_and_b32_e32 v24, 0x7ff, v16
	v_lshlrev_b64 v[18:19], 13, v[16:17]
	v_or_b32_e32 v16, v73, v24
	s_cbranch_vccnz .LBB0_672
	s_and_b64 vcc, exec, s[12:13]
	s_mov_b64 s[6:7], -1
	s_cbranch_vccnz .LBB0_669
	s_andn2_b64 vcc, exec, s[90:91]
	s_cbranch_vccnz .LBB0_666
	s_andn2_b64 vcc, exec, s[88:89]
	s_cbranch_vccnz .LBB0_663
	v_lshl_add_u64 v[20:21], s[20:21], 0, v[18:19]
	v_lshl_add_u64 v[20:21], s[0:1], 1, v[20:21]
	v_lshl_add_u64 v[20:21], v[20:21], 0, v[136:137]
	v_lshl_add_u64 v[22:23], v[20:21], 0, s[30:31]
	s_mov_b64 s[6:7], 0

; __device__ __forceinline__ float rstd_of(const float* ss, int row) { return __builtin_amdgcn_rsqf(ss[row] * (1.0f / 1024.0f) + RMS_EPS); }
;     __device__ __forceinline__ void operator()(const Acc& acc, const Unit& u, int wr, int wc, int fr, int fq) const {
;     ...
;                 const int row = row0 + ai * HALF + m * 16; const float rs = rstd_of(ss, row) * sc;
;                 const int b = row >> 11, t = row & (SEQ - 1);
.LBB0_674:

; __device__ __forceinline__ unsigned cvt_pk_bf16(float lo, float hi) { f32x2_t v = {lo, hi}; bf16x2_t b = __builtin_convertvector(v, bf16x2_t); return __builtin_bit_cast(unsigned, b); }
; __device__ __forceinline__ float rstd_of(const float* ss, int row) { return __builtin_amdgcn_rsqf(ss[row] * (1.0f / 1024.0f) + RMS_EPS); }
; __device__ __forceinline__ float sigmoidf_(float v) { return __builtin_amdgcn_rcpf(1.0f + __builtin_amdgcn_exp2f(-v * LOG2E)); }
;     __device__ __forceinline__ void operator()(const Acc& acc, const Unit& u, int wr, int wc, int fr, int fq) const {
;     ...
;                 const int row = row0 + ai * HALF + m * 16; const float rs = rstd_of(ss, row) * sc;
;                 const int b = row >> 11, t = row & (SEQ - 1);
; #pragma unroll
;                 for (int bj = 0; bj < 2; ++bj) {
;                     float o[8];
; #pragma unroll
;                     for (int n = 0; n < 2; ++n)
; #pragma unroll
;                         for (int e = 0; e < 4; ++e) { float v = acc[ai][bj][m][n][e] * rs; if (isg) v = sigmoidf_(v + bv[bj][4 * n + e]); o[4 * n + e] = v; }
;                     u32x4 w; w.x = cvt_pk_bf16(o[0], o[1]); w.y = cvt_pk_bf16(o[2], o[3]); w.z = cvt_pk_bf16(o[4], o[5]); w.w = cvt_pk_bf16(o[6], o[7]);
;                     bf16_t* dst;
;                     if (tile < 4) dst = P + (size_t)row * PP + C_DQ + tile * BM + bj * HALF + cc;
;                     else if (tile < 8) dst = KD + ((size_t)((b * 8 + (tile - 4) * 2 + bj) * SEQ + t)) * 128 + cc;
;                     else if (tile < 12) dst = P + (size_t)row * PP + C_SQ + (tile - 8) * BM + bj * HALF + cc;
;                     else if (tile == 12) { const int ccf = bj * HALF + cc; dst = KS + ((size_t)((b * 4 + (ccf >> 6)) * SEQ + t)) * 64 + (ccf & 63); }
;                     else dst = P + (size_t)row * PP + C_GA + (tile - 13) * BM + bj * HALF + cc;
;                     *(u32x4*)dst = w;
	v_fmamk_f32 v17, v227, 0x3a800000, v170
	v_rsq_f32_e32 v17, v17
	s_and_b64 vcc, exec, s[14:15]
	s_mov_b64 s[6:7], -1
	v_mul_f32_e32 v17, v153, v17
	v_fmac_f32_e32 v187, v12, v17
	v_fmac_f32_e32 v186, v13, v17
	v_mul_f32_e32 v25, 0xbfb8aa3b, v187
	v_mul_f32_e32 v26, 0xbfb8aa3b, v186
	v_exp_f32_e32 v25, v25
	v_exp_f32_e32 v26, v26
	v_mul_f32_e32 v12, v12, v17
	v_mul_f32_e32 v13, v13, v17
	v_add_f32_e32 v25, 1.0, v25
	v_add_f32_e32 v26, 1.0, v26
	v_rcp_f32_e32 v25, v25
	v_rcp_f32_e32 v26, v26
	v_fmac_f32_e32 v191, v14, v17
	v_fmac_f32_e32 v188, v15, v17
	v_cndmask_b32_e64 v12, v12, v25, s[10:11]
	v_cndmask_b32_e64 v13, v13, v26, s[10:11]
	v_mul_f32_e32 v25, 0xbfb8aa3b, v191
	v_mul_f32_e32 v26, 0xbfb8aa3b, v188
	v_exp_f32_e32 v25, v25
	v_exp_f32_e32 v26, v26
	v_fmac_f32_e32 v192, v8, v17
	v_mul_f32_e32 v27, 0xbfb8aa3b, v192
	v_add_f32_e32 v25, 1.0, v25
	v_add_f32_e32 v26, 1.0, v26
	v_rcp_f32_e32 v25, v25
	v_rcp_f32_e32 v26, v26
	v_exp_f32_e32 v27, v27
	v_mul_f32_e32 v14, v14, v17
	v_mul_f32_e32 v15, v15, v17
	v_fmac_f32_e32 v189, v9, v17
	v_cndmask_b32_e64 v14, v14, v25, s[10:11]
	v_cndmask_b32_e64 v15, v15, v26, s[10:11]
	v_add_f32_e32 v25, 1.0, v27
	v_mul_f32_e32 v26, 0xbfb8aa3b, v189
	v_rcp_f32_e32 v25, v25
	v_exp_f32_e32 v26, v26
	v_mul_f32_e32 v8, v8, v17
	v_fmac_f32_e32 v193, v10, v17
	v_cndmask_b32_e64 v25, v8, v25, s[10:11]
	v_mul_f32_e32 v8, v9, v17
	v_add_f32_e32 v9, 1.0, v26
	v_mul_f32_e32 v26, 0xbfb8aa3b, v193
	v_fmac_f32_e32 v190, v11, v17
	v_rcp_f32_e32 v9, v9
	v_exp_f32_e32 v26, v26
	v_mul_f32_e32 v27, 0xbfb8aa3b, v190
	v_exp_f32_e32 v27, v27
	v_cndmask_b32_e64 v28, v8, v9, s[10:11]
	v_add_f32_e32 v8, 1.0, v26
	v_rcp_f32_e32 v8, v8
	v_add_f32_e32 v9, 1.0, v27
	v_rcp_f32_e32 v9, v9
	v_mul_f32_e32 v10, v10, v17
	v_cndmask_b32_e64 v26, v10, v8, s[10:11]
	v_mul_f32_e32 v8, v11, v17
	v_cndmask_b32_e64 v11, v8, v9, s[10:11]
	v_cvt_pk_bf16_f32 v8, v12, v13
	v_cvt_pk_bf16_f32 v9, v14, v15
	v_cvt_pk_bf16_f32 v10, v25, v28
	v_cvt_pk_bf16_f32 v11, v26, v11
	global_store_dwordx4 v[22:23], v[8:11], off
	s_cbranch_vccnz .LBB0_688
	s_and_b64 vcc, exec, s[12:13]
	s_cbranch_vccnz .LBB0_685
	s_andn2_b64 vcc, exec, s[90:91]
	s_cbranch_vccnz .LBB0_682
	s_andn2_b64 vcc, exec, s[88:89]
	s_cbranch_vccnz .LBB0_679
	v_lshl_add_u64 v[8:9], s[0:1], 1, v[20:21]
	v_lshl_add_u64 v[8:9], v[8:9], 0, v[136:137]
	v_lshl_add_u64 v[8:9], v[8:9], 0, s[36:37]
	s_mov_b64 s[6:7], 0
